# aligned combo12 with write-through (sc1) 16-byte stores in the background weight conversion, so they leave no dirty L2 lines for the barrier write-back
# speedup vs baseline: 1.0019x; 1.0019x over previous
; #define GAS __attribute__((address_space(1)))
; #define LAS __attribute__((address_space(3)))
; #define LDS_WAIT() asm volatile("s_waitcnt lgkmcnt(0)" ::: "memory")
; #define NTLOAD(p) __builtin_nontemporal_load(p)
; __device__ __forceinline__ void cv_item(const float* W, int N, const float* gk, bf16_t* WT, int ldt, int kofs, int drow, int kb, int nb, LAS float* scr, int lane) {
;     const int k0 = 64 * kb, n0 = 32 * nb, kq = lane >> 3, n4 = (lane & 7) * 4;
;     f32x4 v[8]; float sc[8];
; #pragma unroll
;     for (int i = 0; i < 8; ++i) { v[i] = NTLOAD((const GAS f32x4*)(W + (size_t)(k0 + 8 * i + kq) * N + n0 + n4)); sc[i] = gk ? gk[k0 + 8 * i + kq] : 1.0f; }
; #pragma unroll
;     for (int i = 0; i < 8; ++i) { LAS float* d = scr + (8 * i + kq) * 33 + n4; const f32x4 t = v[i] * sc[i]; d[0] = t[0]; d[1] = t[1]; d[2] = t[2]; d[3] = t[3]; }
;     LDS_WAIT(); asm volatile("" ::: "memory");
;     const int c = lane & 7;
; #pragma unroll
;     for (int j = 0; j < 4; ++j) { const int n = (lane >> 3) + 8 * j; const LAS float* s = scr + (8 * c) * 33 + n;
;         u32x4 o; o.x = pk2(s[0 * 33], s[1 * 33]); o.y = pk2(s[2 * 33], s[3 * 33]); o.z = pk2(s[4 * 33], s[5 * 33]); o.w = pk2(s[6 * 33], s[7 * 33]);
;         *(GAS u32x4*)(WT + (size_t)(drow + n) * ldt + kofs + k0 + 8 * c) = o; }
;     LDS_WAIT(); asm volatile("" ::: "memory");
; }
.LBB0_803:
	s_waitcnt vmcnt(7)
	v_pk_mul_f32 v[6:7], v[6:7], v[98:99] op_sel_hi:[1,0]
	v_pk_mul_f32 v[4:5], v[4:5], v[98:99] op_sel_hi:[1,0]
	v_add_u32_e32 v98, v99, v105
	ds_write2_b32 v98, v4, v5 offset1:1
	ds_write2_b32 v98, v6, v7 offset0:2 offset1:3
	s_waitcnt vmcnt(6)
	v_pk_mul_f32 v[4:5], v[10:11], v[2:3] op_sel_hi:[1,0]
	v_pk_mul_f32 v[6:7], v[8:9], v[2:3] op_sel_hi:[1,0]
	v_add_u32_e32 v2, 0x420, v98
	ds_write2_b32 v2, v6, v7 offset1:1
	v_add_u32_e32 v2, 0x428, v98
	ds_write2_b32 v2, v4, v5 offset1:1
	s_waitcnt vmcnt(5)
	v_pk_mul_f32 v[6:7], v[12:13], v[104:105] op_sel_hi:[1,0]
	v_add_u32_e32 v2, 0x840, v98
	v_pk_mul_f32 v[4:5], v[14:15], v[104:105] op_sel_hi:[1,0]
	ds_write2_b32 v2, v6, v7 offset1:1
	v_add_u32_e32 v2, 0x848, v98
	ds_write2_b32 v2, v4, v5 offset1:1
	s_waitcnt vmcnt(4)
	v_pk_mul_f32 v[6:7], v[16:17], v[96:97] op_sel_hi:[1,0]
	v_add_u32_e32 v2, 0xc60, v98
	v_pk_mul_f32 v[4:5], v[18:19], v[96:97] op_sel_hi:[1,0]
	ds_write2_b32 v2, v6, v7 offset1:1
	v_add_u32_e32 v2, 0xc68, v98
	ds_write2_b32 v2, v4, v5 offset1:1
	s_waitcnt vmcnt(3)
	v_pk_mul_f32 v[6:7], v[20:21], v[108:109] op_sel_hi:[1,0]
	v_add_u32_e32 v2, 0x1080, v98
	v_pk_mul_f32 v[4:5], v[22:23], v[108:109] op_sel_hi:[1,0]
	ds_write2_b32 v2, v6, v7 offset1:1
	v_add_u32_e32 v2, 0x1088, v98
	ds_write2_b32 v2, v4, v5 offset1:1
	s_waitcnt vmcnt(2)
	v_pk_mul_f32 v[6:7], v[24:25], v[102:103] op_sel_hi:[1,0]
	v_add_u32_e32 v2, 0x14a0, v98
	v_pk_mul_f32 v[4:5], v[26:27], v[102:103] op_sel_hi:[1,0]
	ds_write2_b32 v2, v6, v7 offset1:1
	v_add_u32_e32 v2, 0x14a8, v98
	ds_write2_b32 v2, v4, v5 offset1:1
	s_waitcnt vmcnt(1)
	v_pk_mul_f32 v[6:7], v[28:29], v[110:111] op_sel_hi:[1,0]
	v_add_u32_e32 v2, 0x18c0, v98
	v_pk_mul_f32 v[4:5], v[30:31], v[110:111] op_sel_hi:[1,0]
	ds_write2_b32 v2, v6, v7 offset1:1
	v_add_u32_e32 v2, 0x18c8, v98
	ds_write2_b32 v2, v4, v5 offset1:1
	s_waitcnt vmcnt(0)
	v_pk_mul_f32 v[6:7], v[32:33], v[106:107] op_sel_hi:[1,0]
	v_add_u32_e32 v2, 0x1ce0, v98
	v_pk_mul_f32 v[4:5], v[34:35], v[106:107] op_sel_hi:[1,0]
	ds_write2_b32 v2, v6, v7 offset1:1
	v_add_u32_e32 v2, 0x1ce8, v98
	ds_write2_b32 v2, v4, v5 offset1:1
	s_waitcnt lgkmcnt(0)
	ds_read2_b32 v[4:5], v103 offset1:33
	s_waitcnt lgkmcnt(0)
	v_cvt_pk_bf16_f32 v4, v4, v5
	ds_read2_b32 v[6:7], v103 offset0:66 offset1:99
	s_waitcnt lgkmcnt(0)
	v_cvt_pk_bf16_f32 v5, v6, v7
	ds_read2_b32 v[6:7], v103 offset0:132 offset1:165
	s_waitcnt lgkmcnt(0)
	v_cvt_pk_bf16_f32 v6, v6, v7
	ds_read2_b32 v[8:9], v103 offset0:198 offset1:231
	s_waitcnt lgkmcnt(0)
	v_cvt_pk_bf16_f32 v7, v8, v9
	v_add_u32_e32 v8, s8, v97
	s_ashr_i32 s5, s4, 31
	v_ashrrev_i32_e32 v9, 31, v8
	v_lshl_add_u64 v[10:11], s[4:5], 1, v[90:91]
	v_lshlrev_b64 v[8:9], 11, v[8:9]
	v_lshl_add_u64 v[8:9], v[10:11], 0, v[8:9]
	ds_read2_b32 v[12:13], v103 offset0:8 offset1:41
	global_store_dwordx4 v[8:9], v[4:7], off sc1
	s_waitcnt lgkmcnt(0)
	s_nop 0
	v_cvt_pk_bf16_f32 v4, v12, v13
	ds_read2_b32 v[6:7], v103 offset0:74 offset1:107
	s_waitcnt lgkmcnt(0)
	v_cvt_pk_bf16_f32 v5, v6, v7
	ds_read2_b32 v[6:7], v103 offset0:140 offset1:173
	s_waitcnt lgkmcnt(0)
	v_cvt_pk_bf16_f32 v6, v6, v7
	ds_read2_b32 v[8:9], v103 offset0:206 offset1:239
	s_waitcnt lgkmcnt(0)
	v_cvt_pk_bf16_f32 v7, v8, v9
	v_add_u32_e32 v8, s8, v107
	v_ashrrev_i32_e32 v9, 31, v8
	v_lshlrev_b64 v[8:9], 11, v[8:9]
	v_lshl_add_u64 v[8:9], v[10:11], 0, v[8:9]
	ds_read2_b32 v[12:13], v103 offset0:16 offset1:49
	global_store_dwordx4 v[8:9], v[4:7], off sc1
	s_waitcnt lgkmcnt(0)
	s_nop 0
	v_cvt_pk_bf16_f32 v4, v12, v13
	ds_read2_b32 v[6:7], v103 offset0:82 offset1:115
	s_waitcnt lgkmcnt(0)
	v_cvt_pk_bf16_f32 v5, v6, v7
	ds_read2_b32 v[6:7], v103 offset0:148 offset1:181
	s_waitcnt lgkmcnt(0)
	v_cvt_pk_bf16_f32 v6, v6, v7
	ds_read2_b32 v[8:9], v103 offset0:214 offset1:247
	s_waitcnt lgkmcnt(0)
	v_cvt_pk_bf16_f32 v7, v8, v9
	v_add_u32_e32 v8, s8, v109
	v_ashrrev_i32_e32 v9, 31, v8
	v_lshlrev_b64 v[8:9], 11, v[8:9]
	v_lshl_add_u64 v[8:9], v[10:11], 0, v[8:9]
	ds_read2_b32 v[12:13], v103 offset0:24 offset1:57
	global_store_dwordx4 v[8:9], v[4:7], off sc1
	s_waitcnt lgkmcnt(0)
	s_nop 0
	v_cvt_pk_bf16_f32 v4, v12, v13
	ds_read2_b32 v[6:7], v103 offset0:90 offset1:123
	s_waitcnt lgkmcnt(0)
	v_cvt_pk_bf16_f32 v5, v6, v7
	ds_read2_b32 v[6:7], v103 offset0:156 offset1:189
	s_waitcnt lgkmcnt(0)
	v_cvt_pk_bf16_f32 v6, v6, v7
	ds_read2_b32 v[8:9], v103 offset0:222 offset1:255
	s_waitcnt lgkmcnt(0)
	v_cvt_pk_bf16_f32 v7, v8, v9
	v_add_u32_e32 v8, s8, v112
	v_ashrrev_i32_e32 v9, 31, v8
	v_lshlrev_b64 v[8:9], 11, v[8:9]
	v_lshl_add_u64 v[8:9], v[10:11], 0, v[8:9]
	global_store_dwordx4 v[8:9], v[4:7], off sc1
	s_waitcnt lgkmcnt(0)

; #define GAS __attribute__((address_space(1)))
; #define LAS __attribute__((address_space(3)))
; #define NTLOAD(p) __builtin_nontemporal_load(p)
; __device__ __forceinline__ void cv_item(const float* W, int N, const float* gk, bf16_t* WT, int ldt, int kofs, int drow, int kb, int nb, LAS float* scr, int lane) {
;     const int k0 = 64 * kb, n0 = 32 * nb, kq = lane >> 3, n4 = (lane & 7) * 4;
;     f32x4 v[8]; float sc[8];
; #pragma unroll
;     for (int i = 0; i < 8; ++i) { v[i] = NTLOAD((const GAS f32x4*)(W + (size_t)(k0 + 8 * i + kq) * N + n0 + n4)); sc[i] = gk ? gk[k0 + 8 * i + kq] : 1.0f; }
; #pragma unroll
; __device__ __forceinline__ void cv_dispatch(const CvPtrs& P, unsigned char* ws, float* out, int layer, int r, LAS float* scr, int lane) {
;     ...
;     if (r < CI_IN) { const int nblk = NIN / 32, kb = r / nblk, nb = r % nblk; cv_item(P.w_in + (size_t)layer * D * NIN, NIN, P.g_mix + layer * D, WB + WB_WIN, D, 0, win_dst(32 * nb), kb, nb, scr, lane); return; } r -= CI_IN;
;     if (r < CI_A)  { const int nblk = D / 32, kb = r / nblk, nb = r % nblk; cv_item(P.w_a + (size_t)layer * DC * D, D, nullptr, WB + WB_WAB, D, 0, 32 * nb, kb, nb, scr, lane); return; } r -= CI_A;
;     if (r < CI_A)  { const int nblk = D / 32, kb = r / nblk, nb = r % nblk; cv_item(P.w_b + (size_t)layer * DSC * D, D, nullptr, WB + WB_WAB, D, DC, 32 * nb, kb, nb, scr, lane); return; } r -= CI_A;
;     if (r < CI_O)  { const int nblk = D / 32, kb = r / nblk, nb = r % nblk; cv_item(P.w_o + (size_t)layer * D * D, D, nullptr, WB + WB_WO, D, 0, 32 * nb, kb, nb, scr, lane); return; } r -= CI_O;
;     if (r < CI_UP) { const int nblk = NUP / 32, kb = r / nblk, nb = r % nblk; cv_item(P.w_up + (size_t)layer * D * NUP, NUP, P.g_ffn + layer * D, WB + WB_WUP, D, 0, wup_dst(32 * nb), kb, nb, scr, lane); return; } r -= CI_UP;
;     if (r < CI_DN) { const int nblk = D / 32, kb = r / nblk, nb = r % nblk; cv_item(P.w_dn + (size_t)layer * DFF * D, D, nullptr, WB0 + WB_WDN, DFF, 0, 32 * nb, kb, nb, scr, lane); return; } r -= CI_DN;
;     if (r < CI_O)  { const int nblk = D / 32, kb = r / nblk, nb = r % nblk; cv_item(P.w_pg + (size_t)layer * D * D, D, P.g_ple + layer * D, WB0 + WB_WPG, D, 0, 32 * nb, kb, nb, scr, lane); return; } r -= CI_O;
;     { const int nblk = D / 32, kb = r / nblk, nb = r % nblk; cv_item(P.w_pl + (size_t)layer * PLE * D, D, nullptr, WB + WB_WPL, PLE, 0, 32 * nb, kb, nb, scr, lane); }
.LBB0_805:
	s_cmpk_gt_i32 s7, 0xeff
	s_mov_b64 s[0:1], -1
	s_cbranch_scc0 .LBB0_939
	s_cmpk_gt_u32 s7, 0x10ff
	s_cbranch_scc0 .LBB0_935
	s_cmpk_gt_u32 s7, 0x187f
	s_cbranch_scc0 .LBB0_913
	s_cmpk_lt_u32 s7, 0x2200
	s_movk_i32 s0, 0xfe00
	s_cselect_b32 s0, s0, 0xffffe700
	s_cmpk_gt_u32 s7, 0x217f
	s_cselect_b32 s4, s0, 0xffffe780
	s_add_i32 s4, s4, s7
	s_cmpk_gt_u32 s4, 0x8ff
	s_mov_b64 s[0:1], -1
	s_cbranch_scc0 .LBB0_870
	s_cmpk_gt_u32 s4, 0x9ff
	s_cbranch_scc0 .LBB0_867
	s_cmpk_gt_u32 s4, 0xaff
	s_cbranch_scc0 .LBB0_864
	s_cmpk_gt_u32 s4, 0xcff
	s_cbranch_scc0 .LBB0_861
	s_cmpk_gt_u32 s4, 0x17ff
	s_cbranch_scc0 .LBB0_838
	s_cmpk_gt_u32 s4, 0x1d7f
	s_cbranch_scc0 .LBB0_835
	s_lshl_b32 s0, s4, 5
	s_and_b32 s5, s0, 0x3e0
	s_lshl_b32 s8, s4, 1
	s_cmpk_gt_u32 s4, 0x1f7f
	s_mov_b64 s[0:1], -1
	v_or_b32_e32 v114, s5, v97
	v_or_b32_e32 v113, s5, v107
	v_or_b32_e32 v111, s5, v109
	v_or_b32_e32 v101, s5, v112
	s_cbranch_scc0 .LBB0_816
	s_and_b32 s0, s8, 0x7fffffc0
	s_addk_i32 s0, 0xc100
	v_readlane_b32 s12, v254, 4
	v_or_b32_e32 v2, s0, v97
	v_readlane_b32 s13, v254, 5
	s_lshl_b32 s12, s5, 2
	v_lshlrev_b64 v[4:5], 12, v[2:3]
	v_lshl_add_u64 v[32:33], v[52:53], 0, s[12:13]
	v_or_b32_e32 v8, 8, v2
	v_mov_b32_e32 v9, v3
	v_lshl_add_u64 v[4:5], v[32:33], 0, v[4:5]
	v_lshlrev_b64 v[8:9], 12, v[8:9]
	global_load_dwordx4 v[4:7], v[4:5], off nt
	v_lshl_add_u64 v[8:9], v[32:33], 0, v[8:9]
	v_or_b32_e32 v12, 16, v2
	v_mov_b32_e32 v13, v3
	global_load_dwordx4 v[8:11], v[8:9], off nt
	v_lshlrev_b64 v[12:13], 12, v[12:13]
	v_lshl_add_u64 v[12:13], v[32:33], 0, v[12:13]
	v_or_b32_e32 v16, 24, v2
	v_mov_b32_e32 v17, v3
	global_load_dwordx4 v[12:15], v[12:13], off nt
	v_lshlrev_b64 v[16:17], 12, v[16:17]
	v_lshl_add_u64 v[16:17], v[32:33], 0, v[16:17]
	v_or_b32_e32 v20, 32, v2
	v_mov_b32_e32 v21, v3
	global_load_dwordx4 v[16:19], v[16:17], off nt
	v_lshlrev_b64 v[20:21], 12, v[20:21]
	v_lshl_add_u64 v[20:21], v[32:33], 0, v[20:21]
	v_or_b32_e32 v24, 40, v2
	v_mov_b32_e32 v25, v3
	global_load_dwordx4 v[20:23], v[20:21], off nt
	v_lshlrev_b64 v[24:25], 12, v[24:25]
	v_lshl_add_u64 v[24:25], v[32:33], 0, v[24:25]
	v_or_b32_e32 v28, 48, v2
	v_mov_b32_e32 v29, v3
	global_load_dwordx4 v[24:27], v[24:25], off nt
	v_lshlrev_b64 v[28:29], 12, v[28:29]
	v_lshl_add_u64 v[28:29], v[32:33], 0, v[28:29]
	v_or_b32_e32 v2, 56, v2
	global_load_dwordx4 v[28:31], v[28:29], off nt
	v_lshlrev_b64 v[34:35], 12, v[2:3]
	v_lshl_add_u64 v[32:33], v[32:33], 0, v[34:35]
	global_load_dwordx4 v[32:35], v[32:33], off nt
	v_add_u32_e32 v2, v99, v105
	s_mov_b32 s1, s13
	v_writelane_b32 v254, s0, 4
	s_waitcnt vmcnt(7)
	ds_write2_b32 v2, v4, v5 offset1:1
	ds_write2_b32 v2, v6, v7 offset0:2 offset1:3
	v_add_u32_e32 v4, 0x420, v2
	v_writelane_b32 v254, s1, 5
	s_mov_b32 s1, s13
	s_waitcnt vmcnt(6)
	ds_write2_b32 v4, v8, v9 offset1:1
	v_add_u32_e32 v4, 0x428, v2
	ds_write2_b32 v4, v10, v11 offset1:1
	v_add_u32_e32 v4, 0x840, v2
	v_lshl_add_u64 v[8:9], s[0:1], 1, v[54:55]
	s_waitcnt vmcnt(5)
	ds_write2_b32 v4, v12, v13 offset1:1
	v_add_u32_e32 v4, 0x848, v2
	ds_write2_b32 v4, v14, v15 offset1:1
	v_add_u32_e32 v4, 0xc60, v2
	s_mov_b64 s[0:1], 0
	s_waitcnt vmcnt(4)
	ds_write2_b32 v4, v16, v17 offset1:1
	v_add_u32_e32 v4, 0xc68, v2
	ds_write2_b32 v4, v18, v19 offset1:1
	v_add_u32_e32 v4, 0x1080, v2
	s_waitcnt vmcnt(3)
	ds_write2_b32 v4, v20, v21 offset1:1
	v_add_u32_e32 v4, 0x1088, v2
	ds_write2_b32 v4, v22, v23 offset1:1
	v_add_u32_e32 v4, 0x14a0, v2
	s_waitcnt vmcnt(2)
	ds_write2_b32 v4, v24, v25 offset1:1
	v_add_u32_e32 v4, 0x14a8, v2
	ds_write2_b32 v4, v26, v27 offset1:1
	v_add_u32_e32 v4, 0x18c0, v2
	s_waitcnt vmcnt(1)
	ds_write2_b32 v4, v28, v29 offset1:1
	v_add_u32_e32 v4, 0x18c8, v2
	ds_write2_b32 v4, v30, v31 offset1:1
	v_add_u32_e32 v4, 0x1ce0, v2
	v_add_u32_e32 v2, 0x1ce8, v2
	s_waitcnt vmcnt(0)
	ds_write2_b32 v4, v32, v33 offset1:1
	ds_write2_b32 v2, v34, v35 offset1:1
	s_waitcnt lgkmcnt(0)
	ds_read2_b32 v[4:5], v103 offset1:33
	s_waitcnt lgkmcnt(0)
	v_cvt_pk_bf16_f32 v4, v4, v5
	ds_read2_b32 v[6:7], v103 offset0:66 offset1:99
	s_waitcnt lgkmcnt(0)
	v_cvt_pk_bf16_f32 v5, v6, v7
	ds_read2_b32 v[6:7], v103 offset0:132 offset1:165
	s_waitcnt lgkmcnt(0)
	v_cvt_pk_bf16_f32 v6, v6, v7
	ds_read2_b32 v[10:11], v103 offset0:198 offset1:231
	v_lshlrev_b32_e32 v2, 9, v114
	s_waitcnt lgkmcnt(0)
	v_cvt_pk_bf16_f32 v7, v10, v11
	v_lshl_add_u64 v[10:11], v[8:9], 0, v[2:3]
	global_store_dwordx4 v[10:11], v[4:7], off sc1
	ds_read2_b32 v[4:5], v103 offset0:8 offset1:41
	v_lshlrev_b32_e32 v2, 9, v113
	s_waitcnt lgkmcnt(0)
	v_cvt_pk_bf16_f32 v4, v4, v5
	ds_read2_b32 v[6:7], v103 offset0:74 offset1:107
	s_waitcnt lgkmcnt(0)
	v_cvt_pk_bf16_f32 v5, v6, v7
	ds_read2_b32 v[6:7], v103 offset0:140 offset1:173
	s_waitcnt lgkmcnt(0)
	v_cvt_pk_bf16_f32 v6, v6, v7
	ds_read2_b32 v[10:11], v103 offset0:206 offset1:239
	s_waitcnt lgkmcnt(0)
	v_cvt_pk_bf16_f32 v7, v10, v11
	v_lshl_add_u64 v[10:11], v[8:9], 0, v[2:3]
	global_store_dwordx4 v[10:11], v[4:7], off sc1
	ds_read2_b32 v[4:5], v103 offset0:16 offset1:49
	v_lshlrev_b32_e32 v2, 9, v111
	s_waitcnt lgkmcnt(0)
	v_cvt_pk_bf16_f32 v4, v4, v5
	ds_read2_b32 v[6:7], v103 offset0:82 offset1:115
	s_waitcnt lgkmcnt(0)
	v_cvt_pk_bf16_f32 v5, v6, v7
	ds_read2_b32 v[6:7], v103 offset0:148 offset1:181
	s_waitcnt lgkmcnt(0)
	v_cvt_pk_bf16_f32 v6, v6, v7
	ds_read2_b32 v[10:11], v103 offset0:214 offset1:247
	s_waitcnt lgkmcnt(0)
	v_cvt_pk_bf16_f32 v7, v10, v11
	v_lshl_add_u64 v[10:11], v[8:9], 0, v[2:3]
	global_store_dwordx4 v[10:11], v[4:7], off sc1
	ds_read2_b32 v[4:5], v103 offset0:24 offset1:57
	v_lshlrev_b32_e32 v2, 9, v101
	s_waitcnt lgkmcnt(0)
	v_cvt_pk_bf16_f32 v4, v4, v5
	ds_read2_b32 v[6:7], v103 offset0:90 offset1:123
	s_waitcnt lgkmcnt(0)
	v_cvt_pk_bf16_f32 v5, v6, v7
	ds_read2_b32 v[6:7], v103 offset0:156 offset1:189
	v_lshl_add_u64 v[8:9], v[8:9], 0, v[2:3]
	s_waitcnt lgkmcnt(0)
	v_cvt_pk_bf16_f32 v6, v6, v7
	ds_read2_b32 v[10:11], v103 offset0:222 offset1:255
	s_waitcnt lgkmcnt(0)
	v_cvt_pk_bf16_f32 v7, v10, v11
	global_store_dwordx4 v[8:9], v[4:7], off sc1
	s_waitcnt lgkmcnt(0)

; #define GAS __attribute__((address_space(1)))
; #define LAS __attribute__((address_space(3)))
; #define LDS_WAIT() asm volatile("s_waitcnt lgkmcnt(0)" ::: "memory")
; #define NTLOAD(p) __builtin_nontemporal_load(p)
; __device__ __forceinline__ void cv_item(const float* W, int N, const float* gk, bf16_t* WT, int ldt, int kofs, int drow, int kb, int nb, LAS float* scr, int lane) {
;     const int k0 = 64 * kb, n0 = 32 * nb, kq = lane >> 3, n4 = (lane & 7) * 4;
;     f32x4 v[8]; float sc[8];
; #pragma unroll
;     for (int i = 0; i < 8; ++i) { v[i] = NTLOAD((const GAS f32x4*)(W + (size_t)(k0 + 8 * i + kq) * N + n0 + n4)); sc[i] = gk ? gk[k0 + 8 * i + kq] : 1.0f; }
; #pragma unroll
;     for (int i = 0; i < 8; ++i) { LAS float* d = scr + (8 * i + kq) * 33 + n4; const f32x4 t = v[i] * sc[i]; d[0] = t[0]; d[1] = t[1]; d[2] = t[2]; d[3] = t[3]; }
;     LDS_WAIT(); asm volatile("" ::: "memory");
;     const int c = lane & 7;
; #pragma unroll
;     for (int j = 0; j < 4; ++j) { const int n = (lane >> 3) + 8 * j; const LAS float* s = scr + (8 * c) * 33 + n;
;         u32x4 o; o.x = pk2(s[0 * 33], s[1 * 33]); o.y = pk2(s[2 * 33], s[3 * 33]); o.z = pk2(s[4 * 33], s[5 * 33]); o.w = pk2(s[6 * 33], s[7 * 33]);
;         *(GAS u32x4*)(WT + (size_t)(drow + n) * ldt + kofs + k0 + 8 * c) = o; }
;     LDS_WAIT(); asm volatile("" ::: "memory");
; }
.LBB0_833:
	s_waitcnt vmcnt(7)
	v_pk_mul_f32 v[6:7], v[6:7], v[98:99] op_sel_hi:[1,0]
	v_pk_mul_f32 v[4:5], v[4:5], v[98:99] op_sel_hi:[1,0]
	v_add_u32_e32 v2, v99, v105
	ds_write2_b32 v2, v4, v5 offset1:1
	ds_write2_b32 v2, v6, v7 offset0:2 offset1:3
	s_waitcnt vmcnt(6)
	v_pk_mul_f32 v[6:7], v[8:9], v[96:97] op_sel_hi:[1,0]
	v_add_u32_e32 v8, 0x420, v2
	v_pk_mul_f32 v[4:5], v[10:11], v[96:97] op_sel_hi:[1,0]
	ds_write2_b32 v8, v6, v7 offset1:1
	v_add_u32_e32 v6, 0x428, v2
	ds_write2_b32 v6, v4, v5 offset1:1
	s_waitcnt vmcnt(5)
	v_pk_mul_f32 v[6:7], v[12:13], v[102:103] op_sel_hi:[1,0]
	v_add_u32_e32 v8, 0x840, v2
	v_pk_mul_f32 v[4:5], v[14:15], v[102:103] op_sel_hi:[1,0]
	ds_write2_b32 v8, v6, v7 offset1:1
	v_add_u32_e32 v6, 0x848, v2
	ds_write2_b32 v6, v4, v5 offset1:1
	s_waitcnt vmcnt(4)
	v_pk_mul_f32 v[6:7], v[16:17], v[100:101] op_sel_hi:[1,0]
	v_add_u32_e32 v8, 0xc60, v2
	v_pk_mul_f32 v[4:5], v[18:19], v[100:101] op_sel_hi:[1,0]
	ds_write2_b32 v8, v6, v7 offset1:1
	v_add_u32_e32 v6, 0xc68, v2
	ds_write2_b32 v6, v4, v5 offset1:1
	s_waitcnt vmcnt(3)
	v_pk_mul_f32 v[6:7], v[20:21], v[106:107] op_sel_hi:[1,0]
	v_add_u32_e32 v8, 0x1080, v2
	v_pk_mul_f32 v[4:5], v[22:23], v[106:107] op_sel_hi:[1,0]
	ds_write2_b32 v8, v6, v7 offset1:1
	v_add_u32_e32 v6, 0x1088, v2
	ds_write2_b32 v6, v4, v5 offset1:1
	s_waitcnt vmcnt(2)
	v_pk_mul_f32 v[6:7], v[24:25], v[104:105] op_sel_hi:[1,0]
	v_add_u32_e32 v8, 0x14a0, v2
	v_pk_mul_f32 v[4:5], v[26:27], v[104:105] op_sel_hi:[1,0]
	ds_write2_b32 v8, v6, v7 offset1:1
	v_add_u32_e32 v6, 0x14a8, v2
	ds_write2_b32 v6, v4, v5 offset1:1
	s_waitcnt vmcnt(1)
	v_pk_mul_f32 v[6:7], v[28:29], v[110:111] op_sel_hi:[1,0]
	v_add_u32_e32 v8, 0x18c0, v2
	v_pk_mul_f32 v[4:5], v[30:31], v[110:111] op_sel_hi:[1,0]
	ds_write2_b32 v8, v6, v7 offset1:1
	v_add_u32_e32 v6, 0x18c8, v2
	ds_write2_b32 v6, v4, v5 offset1:1
	s_waitcnt vmcnt(0)
	v_pk_mul_f32 v[4:5], v[34:35], v[108:109] op_sel_hi:[1,0]
	v_pk_mul_f32 v[6:7], v[32:33], v[108:109] op_sel_hi:[1,0]
	v_add_u32_e32 v8, 0x1ce0, v2
	v_add_u32_e32 v2, 0x1ce8, v2
	ds_write2_b32 v8, v6, v7 offset1:1
	ds_write2_b32 v2, v4, v5 offset1:1
	s_waitcnt lgkmcnt(0)
	v_readlane_b32 s8, v254, 4
	ds_read2_b32 v[4:5], v103 offset1:33
	v_readlane_b32 s9, v254, 5
	s_waitcnt lgkmcnt(0)
	v_cvt_pk_bf16_f32 v4, v4, v5
	ds_read2_b32 v[6:7], v103 offset0:66 offset1:99
	s_mov_b32 s1, s9
	s_waitcnt lgkmcnt(0)
	v_cvt_pk_bf16_f32 v5, v6, v7
	ds_read2_b32 v[6:7], v103 offset0:132 offset1:165
	v_lshl_add_u64 v[10:11], s[0:1], 1, v[58:59]
	v_lshlrev_b32_e32 v2, 11, v114
	s_waitcnt lgkmcnt(0)
	v_cvt_pk_bf16_f32 v6, v6, v7
	ds_read2_b32 v[8:9], v103 offset0:198 offset1:231
	s_waitcnt lgkmcnt(0)
	v_cvt_pk_bf16_f32 v7, v8, v9
	v_lshl_add_u64 v[12:13], v[10:11], 0, v[2:3]
	ds_read2_b32 v[8:9], v103 offset0:8 offset1:41
	global_store_dwordx4 v[12:13], v[4:7], off sc1
	v_lshlrev_b32_e32 v2, 11, v113
	v_lshl_add_u64 v[12:13], v[10:11], 0, v[2:3]
	s_waitcnt lgkmcnt(0)
	v_cvt_pk_bf16_f32 v4, v8, v9
	ds_read2_b32 v[6:7], v103 offset0:74 offset1:107
	s_waitcnt lgkmcnt(0)
	v_cvt_pk_bf16_f32 v5, v6, v7
	ds_read2_b32 v[6:7], v103 offset0:140 offset1:173
	s_waitcnt lgkmcnt(0)
	v_cvt_pk_bf16_f32 v6, v6, v7
	ds_read2_b32 v[8:9], v103 offset0:206 offset1:239
	s_waitcnt lgkmcnt(0)
	v_cvt_pk_bf16_f32 v7, v8, v9
	ds_read2_b32 v[8:9], v103 offset0:16 offset1:49
	global_store_dwordx4 v[12:13], v[4:7], off sc1
	v_lshlrev_b32_e32 v2, 11, v111
	v_lshl_add_u64 v[12:13], v[10:11], 0, v[2:3]
	s_waitcnt lgkmcnt(0)
	v_cvt_pk_bf16_f32 v4, v8, v9
	ds_read2_b32 v[6:7], v103 offset0:82 offset1:115
	s_waitcnt lgkmcnt(0)
	v_cvt_pk_bf16_f32 v5, v6, v7
	ds_read2_b32 v[6:7], v103 offset0:148 offset1:181
	s_waitcnt lgkmcnt(0)
	v_cvt_pk_bf16_f32 v6, v6, v7
	ds_read2_b32 v[8:9], v103 offset0:214 offset1:247
	s_waitcnt lgkmcnt(0)
	v_cvt_pk_bf16_f32 v7, v8, v9
	ds_read2_b32 v[8:9], v103 offset0:24 offset1:57
	global_store_dwordx4 v[12:13], v[4:7], off sc1
	v_lshlrev_b32_e32 v2, 11, v101
	s_waitcnt lgkmcnt(0)
	v_cvt_pk_bf16_f32 v4, v8, v9
	ds_read2_b32 v[6:7], v103 offset0:90 offset1:123
	s_waitcnt lgkmcnt(0)
	v_cvt_pk_bf16_f32 v5, v6, v7
	ds_read2_b32 v[6:7], v103 offset0:156 offset1:189
	s_waitcnt lgkmcnt(0)
	v_cvt_pk_bf16_f32 v6, v6, v7
	ds_read2_b32 v[8:9], v103 offset0:222 offset1:255
	s_waitcnt lgkmcnt(0)
	v_cvt_pk_bf16_f32 v7, v8, v9
	v_lshl_add_u64 v[8:9], v[10:11], 0, v[2:3]
	global_store_dwordx4 v[8:9], v[4:7], off sc1
	s_waitcnt lgkmcnt(0)

; #define GAS __attribute__((address_space(1)))
; #define LAS __attribute__((address_space(3)))
; #define LDS_WAIT() asm volatile("s_waitcnt lgkmcnt(0)" ::: "memory")
; #define NTLOAD(p) __builtin_nontemporal_load(p)
; __device__ __forceinline__ void cv_item(const float* W, int N, const float* gk, bf16_t* WT, int ldt, int kofs, int drow, int kb, int nb, LAS float* scr, int lane) {
;     const int k0 = 64 * kb, n0 = 32 * nb, kq = lane >> 3, n4 = (lane & 7) * 4;
;     f32x4 v[8]; float sc[8];
; #pragma unroll
;     for (int i = 0; i < 8; ++i) { v[i] = NTLOAD((const GAS f32x4*)(W + (size_t)(k0 + 8 * i + kq) * N + n0 + n4)); sc[i] = gk ? gk[k0 + 8 * i + kq] : 1.0f; }
; #pragma unroll
;     for (int i = 0; i < 8; ++i) { LAS float* d = scr + (8 * i + kq) * 33 + n4; const f32x4 t = v[i] * sc[i]; d[0] = t[0]; d[1] = t[1]; d[2] = t[2]; d[3] = t[3]; }
;     LDS_WAIT(); asm volatile("" ::: "memory");
;     const int c = lane & 7;
; #pragma unroll
;     for (int j = 0; j < 4; ++j) { const int n = (lane >> 3) + 8 * j; const LAS float* s = scr + (8 * c) * 33 + n;
;         u32x4 o; o.x = pk2(s[0 * 33], s[1 * 33]); o.y = pk2(s[2 * 33], s[3 * 33]); o.z = pk2(s[4 * 33], s[5 * 33]); o.w = pk2(s[6 * 33], s[7 * 33]);
;         *(GAS u32x4*)(WT + (size_t)(drow + n) * ldt + kofs + k0 + 8 * c) = o; }
;     LDS_WAIT(); asm volatile("" ::: "memory");
; }
; __device__ __forceinline__ void cv_dispatch(const CvPtrs& P, unsigned char* ws, float* out, int layer, int r, LAS float* scr, int lane) {
;     ...
;     if (r < CI_DN) { const int nblk = D / 32, kb = r / nblk, nb = r % nblk; cv_item(P.w_dn + (size_t)layer * DFF * D, D, nullptr, WB0 + WB_WDN, DFF, 0, 32 * nb, kb, nb, scr, lane); return; } r -= CI_DN;
.LBB0_835:
	s_andn2_b64 vcc, exec, s[0:1]
	s_cbranch_vccnz .LBB0_837
	s_lshl_b32 s0, s4, 5
	s_and_b32 s5, s0, 0x3e0
	s_lshl_b32 s0, s4, 1
	s_and_b32 s0, s0, 0x3fc0
	s_addk_i32 s0, 0xd000
	v_readlane_b32 s8, v254, 4
	v_or_b32_e32 v2, s0, v97
	v_readlane_b32 s9, v254, 5
	s_lshl_b32 s8, s5, 2
	v_lshlrev_b64 v[4:5], 12, v[2:3]
	v_lshl_add_u64 v[32:33], v[60:61], 0, s[8:9]
	v_or_b32_e32 v8, 8, v2
	v_mov_b32_e32 v9, v3
	v_lshl_add_u64 v[4:5], v[32:33], 0, v[4:5]
	v_lshlrev_b64 v[8:9], 12, v[8:9]
	global_load_dwordx4 v[4:7], v[4:5], off nt
	v_lshl_add_u64 v[8:9], v[32:33], 0, v[8:9]
	v_or_b32_e32 v12, 16, v2
	v_mov_b32_e32 v13, v3
	global_load_dwordx4 v[8:11], v[8:9], off nt
	v_lshlrev_b64 v[12:13], 12, v[12:13]
	v_lshl_add_u64 v[12:13], v[32:33], 0, v[12:13]
	v_or_b32_e32 v16, 24, v2
	v_mov_b32_e32 v17, v3
	global_load_dwordx4 v[12:15], v[12:13], off nt
	v_lshlrev_b64 v[16:17], 12, v[16:17]
	v_lshl_add_u64 v[16:17], v[32:33], 0, v[16:17]
	v_or_b32_e32 v20, 32, v2
	v_mov_b32_e32 v21, v3
	global_load_dwordx4 v[16:19], v[16:17], off nt
	v_lshlrev_b64 v[20:21], 12, v[20:21]
	v_lshl_add_u64 v[20:21], v[32:33], 0, v[20:21]
	v_or_b32_e32 v24, 40, v2
	v_mov_b32_e32 v25, v3
	global_load_dwordx4 v[20:23], v[20:21], off nt
	v_lshlrev_b64 v[24:25], 12, v[24:25]
	v_lshl_add_u64 v[24:25], v[32:33], 0, v[24:25]
	v_or_b32_e32 v28, 48, v2
	v_mov_b32_e32 v29, v3
	global_load_dwordx4 v[24:27], v[24:25], off nt
	v_lshlrev_b64 v[28:29], 12, v[28:29]
	v_lshl_add_u64 v[28:29], v[32:33], 0, v[28:29]
	v_or_b32_e32 v2, 56, v2
	global_load_dwordx4 v[28:31], v[28:29], off nt
	v_lshlrev_b64 v[34:35], 12, v[2:3]
	v_lshl_add_u64 v[32:33], v[32:33], 0, v[34:35]
	global_load_dwordx4 v[32:35], v[32:33], off nt
	v_add_u32_e32 v2, v99, v105
	s_mov_b32 s1, s9
	v_writelane_b32 v254, s0, 4
	s_waitcnt vmcnt(7)
	ds_write2_b32 v2, v4, v5 offset1:1
	ds_write2_b32 v2, v6, v7 offset0:2 offset1:3
	v_add_u32_e32 v4, 0x420, v2
	v_writelane_b32 v254, s1, 5
	s_mov_b32 s1, s9
	s_waitcnt vmcnt(6)
	ds_write2_b32 v4, v8, v9 offset1:1
	v_add_u32_e32 v4, 0x428, v2
	ds_write2_b32 v4, v10, v11 offset1:1
	v_add_u32_e32 v4, 0x840, v2
	v_lshl_add_u64 v[8:9], s[0:1], 1, v[62:63]
	s_waitcnt vmcnt(5)
	ds_write2_b32 v4, v12, v13 offset1:1
	v_add_u32_e32 v4, 0x848, v2
	ds_write2_b32 v4, v14, v15 offset1:1
	v_add_u32_e32 v4, 0xc60, v2
	s_waitcnt vmcnt(4)
	ds_write2_b32 v4, v16, v17 offset1:1
	v_add_u32_e32 v4, 0xc68, v2
	ds_write2_b32 v4, v18, v19 offset1:1
	v_add_u32_e32 v4, 0x1080, v2
	s_waitcnt vmcnt(3)
	ds_write2_b32 v4, v20, v21 offset1:1
	v_add_u32_e32 v4, 0x1088, v2
	ds_write2_b32 v4, v22, v23 offset1:1
	v_add_u32_e32 v4, 0x14a0, v2
	s_waitcnt vmcnt(2)
	ds_write2_b32 v4, v24, v25 offset1:1
	v_add_u32_e32 v4, 0x14a8, v2
	ds_write2_b32 v4, v26, v27 offset1:1
	v_add_u32_e32 v4, 0x18c0, v2
	s_waitcnt vmcnt(1)
	ds_write2_b32 v4, v28, v29 offset1:1
	v_add_u32_e32 v4, 0x18c8, v2
	ds_write2_b32 v4, v30, v31 offset1:1
	v_add_u32_e32 v4, 0x1ce0, v2
	v_add_u32_e32 v2, 0x1ce8, v2
	s_waitcnt vmcnt(0)
	ds_write2_b32 v4, v32, v33 offset1:1
	ds_write2_b32 v2, v34, v35 offset1:1
	s_waitcnt lgkmcnt(0)
	ds_read2_b32 v[4:5], v103 offset1:33
	s_waitcnt lgkmcnt(0)
	v_cvt_pk_bf16_f32 v4, v4, v5
	ds_read2_b32 v[6:7], v103 offset0:66 offset1:99
	s_waitcnt lgkmcnt(0)
	v_cvt_pk_bf16_f32 v5, v6, v7
	ds_read2_b32 v[6:7], v103 offset0:132 offset1:165
	v_or_b32_e32 v2, s5, v97
	s_waitcnt lgkmcnt(0)
	v_cvt_pk_bf16_f32 v6, v6, v7
	ds_read2_b32 v[10:11], v103 offset0:198 offset1:231
	v_mul_u32_u24_e32 v2, 0x1600, v2
	s_waitcnt lgkmcnt(0)
	v_cvt_pk_bf16_f32 v7, v10, v11
	v_lshl_add_u64 v[10:11], v[8:9], 0, v[2:3]
	global_store_dwordx4 v[10:11], v[4:7], off sc1
	ds_read2_b32 v[4:5], v103 offset0:8 offset1:41
	v_or_b32_e32 v2, s5, v107
	s_waitcnt lgkmcnt(0)
	v_cvt_pk_bf16_f32 v4, v4, v5
	ds_read2_b32 v[6:7], v103 offset0:74 offset1:107
	s_waitcnt lgkmcnt(0)
	v_cvt_pk_bf16_f32 v5, v6, v7
	ds_read2_b32 v[6:7], v103 offset0:140 offset1:173
	s_waitcnt lgkmcnt(0)
	v_cvt_pk_bf16_f32 v6, v6, v7
	ds_read2_b32 v[10:11], v103 offset0:206 offset1:239
	v_mul_u32_u24_e32 v2, 0x1600, v2
	s_waitcnt lgkmcnt(0)
	v_cvt_pk_bf16_f32 v7, v10, v11
	v_lshl_add_u64 v[10:11], v[8:9], 0, v[2:3]
	global_store_dwordx4 v[10:11], v[4:7], off sc1
	ds_read2_b32 v[4:5], v103 offset0:16 offset1:49
	v_or_b32_e32 v2, s5, v109
	s_waitcnt lgkmcnt(0)
	v_cvt_pk_bf16_f32 v4, v4, v5
	ds_read2_b32 v[6:7], v103 offset0:82 offset1:115
	s_waitcnt lgkmcnt(0)
	v_cvt_pk_bf16_f32 v5, v6, v7
	ds_read2_b32 v[6:7], v103 offset0:148 offset1:181
	s_waitcnt lgkmcnt(0)
	v_cvt_pk_bf16_f32 v6, v6, v7
	ds_read2_b32 v[10:11], v103 offset0:214 offset1:247
	v_mul_u32_u24_e32 v2, 0x1600, v2
	s_waitcnt lgkmcnt(0)
	v_cvt_pk_bf16_f32 v7, v10, v11
	v_lshl_add_u64 v[10:11], v[8:9], 0, v[2:3]
	global_store_dwordx4 v[10:11], v[4:7], off sc1
	ds_read2_b32 v[4:5], v103 offset0:24 offset1:57
	v_or_b32_e32 v2, s5, v112
	s_waitcnt lgkmcnt(0)
	v_cvt_pk_bf16_f32 v4, v4, v5
	ds_read2_b32 v[6:7], v103 offset0:90 offset1:123
	v_mul_u32_u24_e32 v2, 0x1600, v2
	s_waitcnt lgkmcnt(0)
	v_cvt_pk_bf16_f32 v5, v6, v7
	ds_read2_b32 v[6:7], v103 offset0:156 offset1:189
	v_lshl_add_u64 v[8:9], v[8:9], 0, v[2:3]
	s_waitcnt lgkmcnt(0)
	v_cvt_pk_bf16_f32 v6, v6, v7
	ds_read2_b32 v[10:11], v103 offset0:222 offset1:255
	s_waitcnt lgkmcnt(0)
	v_cvt_pk_bf16_f32 v7, v10, v11
	global_store_dwordx4 v[8:9], v[4:7], off sc1
	s_waitcnt lgkmcnt(0)

; #define GAS __attribute__((address_space(1)))
; #define LAS __attribute__((address_space(3)))
; #define LDS_WAIT() asm volatile("s_waitcnt lgkmcnt(0)" ::: "memory")
; #define NTLOAD(p) __builtin_nontemporal_load(p)
; __device__ __forceinline__ void cv_item(const float* W, int N, const float* gk, bf16_t* WT, int ldt, int kofs, int drow, int kb, int nb, LAS float* scr, int lane) {
;     const int k0 = 64 * kb, n0 = 32 * nb, kq = lane >> 3, n4 = (lane & 7) * 4;
;     f32x4 v[8]; float sc[8];
; #pragma unroll
;     for (int i = 0; i < 8; ++i) { v[i] = NTLOAD((const GAS f32x4*)(W + (size_t)(k0 + 8 * i + kq) * N + n0 + n4)); sc[i] = gk ? gk[k0 + 8 * i + kq] : 1.0f; }
; #pragma unroll
;     for (int i = 0; i < 8; ++i) { LAS float* d = scr + (8 * i + kq) * 33 + n4; const f32x4 t = v[i] * sc[i]; d[0] = t[0]; d[1] = t[1]; d[2] = t[2]; d[3] = t[3]; }
;     LDS_WAIT(); asm volatile("" ::: "memory");
;     const int c = lane & 7;
; #pragma unroll
;     for (int j = 0; j < 4; ++j) { const int n = (lane >> 3) + 8 * j; const LAS float* s = scr + (8 * c) * 33 + n;
;         u32x4 o; o.x = pk2(s[0 * 33], s[1 * 33]); o.y = pk2(s[2 * 33], s[3 * 33]); o.z = pk2(s[4 * 33], s[5 * 33]); o.w = pk2(s[6 * 33], s[7 * 33]);
;         *(GAS u32x4*)(WT + (size_t)(drow + n) * ldt + kofs + k0 + 8 * c) = o; }
;     LDS_WAIT(); asm volatile("" ::: "memory");
; }
.LBB0_859:
	s_waitcnt vmcnt(7)
	v_pk_mul_f32 v[6:7], v[6:7], v[96:97] op_sel_hi:[1,0]
	v_pk_mul_f32 v[4:5], v[4:5], v[96:97] op_sel_hi:[1,0]
	v_add_u32_e32 v96, v99, v105
	ds_write2_b32 v96, v4, v5 offset1:1
	ds_write2_b32 v96, v6, v7 offset0:2 offset1:3
	s_waitcnt vmcnt(6)
	v_pk_mul_f32 v[4:5], v[10:11], v[2:3] op_sel_hi:[1,0]
	v_pk_mul_f32 v[6:7], v[8:9], v[2:3] op_sel_hi:[1,0]
	v_add_u32_e32 v2, 0x420, v96
	ds_write2_b32 v2, v6, v7 offset1:1
	v_add_u32_e32 v2, 0x428, v96
	ds_write2_b32 v2, v4, v5 offset1:1
	s_waitcnt vmcnt(5)
	v_pk_mul_f32 v[6:7], v[12:13], v[100:101] op_sel_hi:[1,0]
	v_add_u32_e32 v2, 0x840, v96
	v_pk_mul_f32 v[4:5], v[14:15], v[100:101] op_sel_hi:[1,0]
	ds_write2_b32 v2, v6, v7 offset1:1
	v_add_u32_e32 v2, 0x848, v96
	ds_write2_b32 v2, v4, v5 offset1:1
	s_waitcnt vmcnt(4)
	v_pk_mul_f32 v[6:7], v[16:17], v[98:99] op_sel_hi:[1,0]
	v_add_u32_e32 v2, 0xc60, v96
	v_pk_mul_f32 v[4:5], v[18:19], v[98:99] op_sel_hi:[1,0]
	ds_write2_b32 v2, v6, v7 offset1:1
	v_add_u32_e32 v2, 0xc68, v96
	ds_write2_b32 v2, v4, v5 offset1:1
	s_waitcnt vmcnt(3)
	v_pk_mul_f32 v[6:7], v[20:21], v[104:105] op_sel_hi:[1,0]
	v_add_u32_e32 v2, 0x1080, v96
	v_pk_mul_f32 v[4:5], v[22:23], v[104:105] op_sel_hi:[1,0]
	ds_write2_b32 v2, v6, v7 offset1:1
	v_add_u32_e32 v2, 0x1088, v96
	ds_write2_b32 v2, v4, v5 offset1:1
	s_waitcnt vmcnt(2)
	v_pk_mul_f32 v[6:7], v[24:25], v[102:103] op_sel_hi:[1,0]
	v_add_u32_e32 v2, 0x14a0, v96
	v_pk_mul_f32 v[4:5], v[26:27], v[102:103] op_sel_hi:[1,0]
	ds_write2_b32 v2, v6, v7 offset1:1
	v_add_u32_e32 v2, 0x14a8, v96
	ds_write2_b32 v2, v4, v5 offset1:1
	s_waitcnt vmcnt(1)
	v_pk_mul_f32 v[6:7], v[28:29], v[108:109] op_sel_hi:[1,0]
	v_add_u32_e32 v2, 0x18c0, v96
	v_pk_mul_f32 v[4:5], v[30:31], v[108:109] op_sel_hi:[1,0]
	ds_write2_b32 v2, v6, v7 offset1:1
	v_add_u32_e32 v2, 0x18c8, v96
	ds_write2_b32 v2, v4, v5 offset1:1
	s_waitcnt vmcnt(0)
	v_pk_mul_f32 v[6:7], v[32:33], v[106:107] op_sel_hi:[1,0]
	v_add_u32_e32 v2, 0x1ce0, v96
	v_pk_mul_f32 v[4:5], v[34:35], v[106:107] op_sel_hi:[1,0]
	ds_write2_b32 v2, v6, v7 offset1:1
	v_add_u32_e32 v2, 0x1ce8, v96
	ds_write2_b32 v2, v4, v5 offset1:1
	s_waitcnt lgkmcnt(0)
	ds_read2_b32 v[4:5], v103 offset1:33
	s_and_b32 s0, 0xffff, s8
	s_waitcnt lgkmcnt(0)
	v_cvt_pk_bf16_f32 v4, v4, v5
	ds_read2_b32 v[6:7], v103 offset0:66 offset1:99
	s_mov_b32 s9, s15
	s_lshl_b32 s8, s0, 1
	v_add_u32_e32 v2, s5, v97
	s_waitcnt lgkmcnt(0)
	v_cvt_pk_bf16_f32 v5, v6, v7
	ds_read2_b32 v[6:7], v103 offset0:132 offset1:165
	v_lshl_add_u64 v[10:11], v[66:67], 0, s[8:9]
	v_lshlrev_b64 v[12:13], 11, v[2:3]
	s_waitcnt lgkmcnt(0)
	v_cvt_pk_bf16_f32 v6, v6, v7
	ds_read2_b32 v[8:9], v103 offset0:198 offset1:231
	s_waitcnt lgkmcnt(0)
	v_cvt_pk_bf16_f32 v7, v8, v9
	v_lshl_add_u64 v[12:13], v[10:11], 0, v[12:13]
	ds_read2_b32 v[8:9], v103 offset0:8 offset1:41
	global_store_dwordx4 v[12:13], v[4:7], off sc1
	v_add_u32_e32 v2, s5, v107
	v_lshlrev_b64 v[12:13], 11, v[2:3]
	s_waitcnt lgkmcnt(0)
	v_cvt_pk_bf16_f32 v4, v8, v9
	ds_read2_b32 v[6:7], v103 offset0:74 offset1:107
	s_waitcnt lgkmcnt(0)
	v_cvt_pk_bf16_f32 v5, v6, v7
	ds_read2_b32 v[6:7], v103 offset0:140 offset1:173
	s_waitcnt lgkmcnt(0)
	v_cvt_pk_bf16_f32 v6, v6, v7
	ds_read2_b32 v[8:9], v103 offset0:206 offset1:239
	s_waitcnt lgkmcnt(0)
	v_cvt_pk_bf16_f32 v7, v8, v9
	v_lshl_add_u64 v[12:13], v[10:11], 0, v[12:13]
	ds_read2_b32 v[8:9], v103 offset0:16 offset1:49
	global_store_dwordx4 v[12:13], v[4:7], off sc1
	v_add_u32_e32 v2, s5, v109
	v_lshlrev_b64 v[12:13], 11, v[2:3]
	s_waitcnt lgkmcnt(0)
	v_cvt_pk_bf16_f32 v4, v8, v9
	ds_read2_b32 v[6:7], v103 offset0:82 offset1:115
	s_waitcnt lgkmcnt(0)
	v_cvt_pk_bf16_f32 v5, v6, v7
	ds_read2_b32 v[6:7], v103 offset0:148 offset1:181
	s_waitcnt lgkmcnt(0)
	v_cvt_pk_bf16_f32 v6, v6, v7
	ds_read2_b32 v[8:9], v103 offset0:214 offset1:247
	s_waitcnt lgkmcnt(0)
	v_cvt_pk_bf16_f32 v7, v8, v9
	v_lshl_add_u64 v[12:13], v[10:11], 0, v[12:13]
	ds_read2_b32 v[8:9], v103 offset0:24 offset1:57
	global_store_dwordx4 v[12:13], v[4:7], off sc1
	v_add_u32_e32 v2, s5, v112
	s_mov_b32 s1, s15
	s_waitcnt lgkmcnt(0)
	v_cvt_pk_bf16_f32 v4, v8, v9
	ds_read2_b32 v[6:7], v103 offset0:90 offset1:123
	s_waitcnt lgkmcnt(0)
	v_cvt_pk_bf16_f32 v5, v6, v7
	ds_read2_b32 v[6:7], v103 offset0:156 offset1:189
	s_waitcnt lgkmcnt(0)
	v_cvt_pk_bf16_f32 v6, v6, v7
	ds_read2_b32 v[8:9], v103 offset0:222 offset1:255
	s_waitcnt lgkmcnt(0)
	v_cvt_pk_bf16_f32 v7, v8, v9
	v_lshlrev_b64 v[8:9], 11, v[2:3]
	v_lshl_add_u64 v[8:9], v[10:11], 0, v[8:9]
	global_store_dwordx4 v[8:9], v[4:7], off sc1
	s_waitcnt lgkmcnt(0)
	v_writelane_b32 v254, s0, 4
	s_nop 1
	v_writelane_b32 v254, s1, 5

; #define GAS __attribute__((address_space(1)))
; #define LAS __attribute__((address_space(3)))
; #define LDS_WAIT() asm volatile("s_waitcnt lgkmcnt(0)" ::: "memory")
; #define NTLOAD(p) __builtin_nontemporal_load(p)
; __device__ __forceinline__ void cv_item(const float* W, int N, const float* gk, bf16_t* WT, int ldt, int kofs, int drow, int kb, int nb, LAS float* scr, int lane) {
;     const int k0 = 64 * kb, n0 = 32 * nb, kq = lane >> 3, n4 = (lane & 7) * 4;
;     f32x4 v[8]; float sc[8];
; #pragma unroll
;     for (int i = 0; i < 8; ++i) { v[i] = NTLOAD((const GAS f32x4*)(W + (size_t)(k0 + 8 * i + kq) * N + n0 + n4)); sc[i] = gk ? gk[k0 + 8 * i + kq] : 1.0f; }
; #pragma unroll
;     for (int i = 0; i < 8; ++i) { LAS float* d = scr + (8 * i + kq) * 33 + n4; const f32x4 t = v[i] * sc[i]; d[0] = t[0]; d[1] = t[1]; d[2] = t[2]; d[3] = t[3]; }
;     LDS_WAIT(); asm volatile("" ::: "memory");
;     const int c = lane & 7;
; #pragma unroll
;     for (int j = 0; j < 4; ++j) { const int n = (lane >> 3) + 8 * j; const LAS float* s = scr + (8 * c) * 33 + n;
;         u32x4 o; o.x = pk2(s[0 * 33], s[1 * 33]); o.y = pk2(s[2 * 33], s[3 * 33]); o.z = pk2(s[4 * 33], s[5 * 33]); o.w = pk2(s[6 * 33], s[7 * 33]);
;         *(GAS u32x4*)(WT + (size_t)(drow + n) * ldt + kofs + k0 + 8 * c) = o; }
;     LDS_WAIT(); asm volatile("" ::: "memory");
; }
; __device__ __forceinline__ void cv_dispatch(const CvPtrs& P, unsigned char* ws, float* out, int layer, int r, LAS float* scr, int lane) {
;     ...
;     if (r < CI_A)  { const int nblk = D / 32, kb = r / nblk, nb = r % nblk; cv_item(P.w_a + (size_t)layer * DC * D, D, nullptr, WB + WB_WAB, D, 0, 32 * nb, kb, nb, scr, lane); return; } r -= CI_A;
;     if (r < CI_A)  { const int nblk = D / 32, kb = r / nblk, nb = r % nblk; cv_item(P.w_b + (size_t)layer * DSC * D, D, nullptr, WB + WB_WAB, D, DC, 32 * nb, kb, nb, scr, lane); return; } r -= CI_A;
;     if (r < CI_O)  { const int nblk = D / 32, kb = r / nblk, nb = r % nblk; cv_item(P.w_o + (size_t)layer * D * D, D, nullptr, WB + WB_WO, D, 0, 32 * nb, kb, nb, scr, lane); return; } r -= CI_O;
.LBB0_861:
	s_andn2_b64 vcc, exec, s[0:1]
	s_cbranch_vccnz .LBB0_863
	s_lshl_b32 s0, s4, 5
	s_and_b32 s5, s0, 0x3e0
	s_lshl_b32 s0, s4, 1
	s_and_b32 s0, s0, 0x1fc0
	s_addk_i32 s0, 0xea00
	v_readlane_b32 s8, v254, 4
	v_or_b32_e32 v2, s0, v97
	v_readlane_b32 s9, v254, 5
	s_lshl_b32 s8, s5, 2
	v_lshlrev_b64 v[4:5], 12, v[2:3]
	v_lshl_add_u64 v[32:33], v[68:69], 0, s[8:9]
	v_or_b32_e32 v8, 8, v2
	v_mov_b32_e32 v9, v3
	v_lshl_add_u64 v[4:5], v[32:33], 0, v[4:5]
	v_lshlrev_b64 v[8:9], 12, v[8:9]
	global_load_dwordx4 v[4:7], v[4:5], off nt
	v_lshl_add_u64 v[8:9], v[32:33], 0, v[8:9]
	v_or_b32_e32 v12, 16, v2
	v_mov_b32_e32 v13, v3
	global_load_dwordx4 v[8:11], v[8:9], off nt
	v_lshlrev_b64 v[12:13], 12, v[12:13]
	v_lshl_add_u64 v[12:13], v[32:33], 0, v[12:13]
	v_or_b32_e32 v16, 24, v2
	v_mov_b32_e32 v17, v3
	global_load_dwordx4 v[12:15], v[12:13], off nt
	v_lshlrev_b64 v[16:17], 12, v[16:17]
	v_lshl_add_u64 v[16:17], v[32:33], 0, v[16:17]
	v_or_b32_e32 v20, 32, v2
	v_mov_b32_e32 v21, v3
	global_load_dwordx4 v[16:19], v[16:17], off nt
	v_lshlrev_b64 v[20:21], 12, v[20:21]
	v_lshl_add_u64 v[20:21], v[32:33], 0, v[20:21]
	v_or_b32_e32 v24, 40, v2
	v_mov_b32_e32 v25, v3
	global_load_dwordx4 v[20:23], v[20:21], off nt
	v_lshlrev_b64 v[24:25], 12, v[24:25]
	v_lshl_add_u64 v[24:25], v[32:33], 0, v[24:25]
	v_or_b32_e32 v28, 48, v2
	v_mov_b32_e32 v29, v3
	global_load_dwordx4 v[24:27], v[24:25], off nt
	v_lshlrev_b64 v[28:29], 12, v[28:29]
	v_lshl_add_u64 v[28:29], v[32:33], 0, v[28:29]
	v_or_b32_e32 v2, 56, v2
	global_load_dwordx4 v[28:31], v[28:29], off nt
	v_lshlrev_b64 v[34:35], 12, v[2:3]
	v_lshl_add_u64 v[32:33], v[32:33], 0, v[34:35]
	global_load_dwordx4 v[32:35], v[32:33], off nt
	v_add_u32_e32 v2, v99, v105
	s_mov_b32 s1, s9
	v_writelane_b32 v254, s0, 4
	s_waitcnt vmcnt(7)
	ds_write2_b32 v2, v4, v5 offset1:1
	ds_write2_b32 v2, v6, v7 offset0:2 offset1:3
	v_add_u32_e32 v4, 0x420, v2
	v_writelane_b32 v254, s1, 5
	s_mov_b32 s1, s9
	s_waitcnt vmcnt(6)
	ds_write2_b32 v4, v8, v9 offset1:1
	v_add_u32_e32 v4, 0x428, v2
	ds_write2_b32 v4, v10, v11 offset1:1
	v_add_u32_e32 v4, 0x840, v2
	v_lshl_add_u64 v[8:9], s[0:1], 1, v[70:71]
	s_waitcnt vmcnt(5)
	ds_write2_b32 v4, v12, v13 offset1:1
	v_add_u32_e32 v4, 0x848, v2
	ds_write2_b32 v4, v14, v15 offset1:1
	v_add_u32_e32 v4, 0xc60, v2
	s_waitcnt vmcnt(4)
	ds_write2_b32 v4, v16, v17 offset1:1
	v_add_u32_e32 v4, 0xc68, v2
	ds_write2_b32 v4, v18, v19 offset1:1
	v_add_u32_e32 v4, 0x1080, v2
	s_waitcnt vmcnt(3)
	ds_write2_b32 v4, v20, v21 offset1:1
	v_add_u32_e32 v4, 0x1088, v2
	ds_write2_b32 v4, v22, v23 offset1:1
	v_add_u32_e32 v4, 0x14a0, v2
	s_waitcnt vmcnt(2)
	ds_write2_b32 v4, v24, v25 offset1:1
	v_add_u32_e32 v4, 0x14a8, v2
	ds_write2_b32 v4, v26, v27 offset1:1
	v_add_u32_e32 v4, 0x18c0, v2
	s_waitcnt vmcnt(1)
	ds_write2_b32 v4, v28, v29 offset1:1
	v_add_u32_e32 v4, 0x18c8, v2
	ds_write2_b32 v4, v30, v31 offset1:1
	v_add_u32_e32 v4, 0x1ce0, v2
	v_add_u32_e32 v2, 0x1ce8, v2
	s_waitcnt vmcnt(0)
	ds_write2_b32 v4, v32, v33 offset1:1
	ds_write2_b32 v2, v34, v35 offset1:1
	s_waitcnt lgkmcnt(0)
	ds_read2_b32 v[4:5], v103 offset1:33
	s_waitcnt lgkmcnt(0)
	v_cvt_pk_bf16_f32 v4, v4, v5
	ds_read2_b32 v[6:7], v103 offset0:66 offset1:99
	s_waitcnt lgkmcnt(0)
	v_cvt_pk_bf16_f32 v5, v6, v7
	ds_read2_b32 v[6:7], v103 offset0:132 offset1:165
	v_or_b32_e32 v2, s5, v97
	s_waitcnt lgkmcnt(0)
	v_cvt_pk_bf16_f32 v6, v6, v7
	ds_read2_b32 v[10:11], v103 offset0:198 offset1:231
	v_lshlrev_b32_e32 v2, 11, v2
	s_waitcnt lgkmcnt(0)
	v_cvt_pk_bf16_f32 v7, v10, v11
	v_lshl_add_u64 v[10:11], v[8:9], 0, v[2:3]
	global_store_dwordx4 v[10:11], v[4:7], off sc1
	ds_read2_b32 v[4:5], v103 offset0:8 offset1:41
	v_or_b32_e32 v2, s5, v107
	s_waitcnt lgkmcnt(0)
	v_cvt_pk_bf16_f32 v4, v4, v5
	ds_read2_b32 v[6:7], v103 offset0:74 offset1:107
	s_waitcnt lgkmcnt(0)
	v_cvt_pk_bf16_f32 v5, v6, v7
	ds_read2_b32 v[6:7], v103 offset0:140 offset1:173
	s_waitcnt lgkmcnt(0)
	v_cvt_pk_bf16_f32 v6, v6, v7
	ds_read2_b32 v[10:11], v103 offset0:206 offset1:239
	v_lshlrev_b32_e32 v2, 11, v2
	s_waitcnt lgkmcnt(0)
	v_cvt_pk_bf16_f32 v7, v10, v11
	v_lshl_add_u64 v[10:11], v[8:9], 0, v[2:3]
	global_store_dwordx4 v[10:11], v[4:7], off sc1
	ds_read2_b32 v[4:5], v103 offset0:16 offset1:49
	v_or_b32_e32 v2, s5, v109
	s_waitcnt lgkmcnt(0)
	v_cvt_pk_bf16_f32 v4, v4, v5
	ds_read2_b32 v[6:7], v103 offset0:82 offset1:115
	s_waitcnt lgkmcnt(0)
	v_cvt_pk_bf16_f32 v5, v6, v7
	ds_read2_b32 v[6:7], v103 offset0:148 offset1:181
	s_waitcnt lgkmcnt(0)
	v_cvt_pk_bf16_f32 v6, v6, v7
	ds_read2_b32 v[10:11], v103 offset0:214 offset1:247
	v_lshlrev_b32_e32 v2, 11, v2
	s_waitcnt lgkmcnt(0)
	v_cvt_pk_bf16_f32 v7, v10, v11
	v_lshl_add_u64 v[10:11], v[8:9], 0, v[2:3]
	global_store_dwordx4 v[10:11], v[4:7], off sc1
	ds_read2_b32 v[4:5], v103 offset0:24 offset1:57
	v_or_b32_e32 v2, s5, v112
	s_waitcnt lgkmcnt(0)
	v_cvt_pk_bf16_f32 v4, v4, v5
	ds_read2_b32 v[6:7], v103 offset0:90 offset1:123
	v_lshlrev_b32_e32 v2, 11, v2
	s_waitcnt lgkmcnt(0)
	v_cvt_pk_bf16_f32 v5, v6, v7
	ds_read2_b32 v[6:7], v103 offset0:156 offset1:189
	v_lshl_add_u64 v[8:9], v[8:9], 0, v[2:3]
	s_waitcnt lgkmcnt(0)
	v_cvt_pk_bf16_f32 v6, v6, v7
	ds_read2_b32 v[10:11], v103 offset0:222 offset1:255
	s_waitcnt lgkmcnt(0)
	v_cvt_pk_bf16_f32 v7, v10, v11
	global_store_dwordx4 v[8:9], v[4:7], off sc1
	s_waitcnt lgkmcnt(0)

; #define GAS __attribute__((address_space(1)))
; #define LAS __attribute__((address_space(3)))
; #define LDS_WAIT() asm volatile("s_waitcnt lgkmcnt(0)" ::: "memory")
; #define NTLOAD(p) __builtin_nontemporal_load(p)
; __device__ __forceinline__ void cv_item(const float* W, int N, const float* gk, bf16_t* WT, int ldt, int kofs, int drow, int kb, int nb, LAS float* scr, int lane) {
;     const int k0 = 64 * kb, n0 = 32 * nb, kq = lane >> 3, n4 = (lane & 7) * 4;
;     f32x4 v[8]; float sc[8];
; #pragma unroll
;     for (int i = 0; i < 8; ++i) { v[i] = NTLOAD((const GAS f32x4*)(W + (size_t)(k0 + 8 * i + kq) * N + n0 + n4)); sc[i] = gk ? gk[k0 + 8 * i + kq] : 1.0f; }
; #pragma unroll
;     for (int i = 0; i < 8; ++i) { LAS float* d = scr + (8 * i + kq) * 33 + n4; const f32x4 t = v[i] * sc[i]; d[0] = t[0]; d[1] = t[1]; d[2] = t[2]; d[3] = t[3]; }
;     LDS_WAIT(); asm volatile("" ::: "memory");
;     const int c = lane & 7;
; #pragma unroll
;     for (int j = 0; j < 4; ++j) { const int n = (lane >> 3) + 8 * j; const LAS float* s = scr + (8 * c) * 33 + n;
;         u32x4 o; o.x = pk2(s[0 * 33], s[1 * 33]); o.y = pk2(s[2 * 33], s[3 * 33]); o.z = pk2(s[4 * 33], s[5 * 33]); o.w = pk2(s[6 * 33], s[7 * 33]);
;         *(GAS u32x4*)(WT + (size_t)(drow + n) * ldt + kofs + k0 + 8 * c) = o; }
;     LDS_WAIT(); asm volatile("" ::: "memory");
; }
; __device__ __forceinline__ void cv_dispatch(const CvPtrs& P, unsigned char* ws, float* out, int layer, int r, LAS float* scr, int lane) {
;     ...
;     if (r < CI_A)  { const int nblk = D / 32, kb = r / nblk, nb = r % nblk; cv_item(P.w_a + (size_t)layer * DC * D, D, nullptr, WB + WB_WAB, D, 0, 32 * nb, kb, nb, scr, lane); return; } r -= CI_A;
;     if (r < CI_A)  { const int nblk = D / 32, kb = r / nblk, nb = r % nblk; cv_item(P.w_b + (size_t)layer * DSC * D, D, nullptr, WB + WB_WAB, D, DC, 32 * nb, kb, nb, scr, lane); return; } r -= CI_A;
;     if (r < CI_O)  { const int nblk = D / 32, kb = r / nblk, nb = r % nblk; cv_item(P.w_o + (size_t)layer * D * D, D, nullptr, WB + WB_WO, D, 0, 32 * nb, kb, nb, scr, lane); return; } r -= CI_O;
.LBB0_864:
	s_andn2_b64 vcc, exec, s[0:1]
	s_cbranch_vccnz .LBB0_866
	s_lshl_b32 s0, s4, 5
	s_and_b32 s5, s0, 0x3e0
	s_lshl_b32 s0, s4, 1
	s_and_b32 s0, s0, 0x1fc0
	s_addk_i32 s0, 0xec00
	v_readlane_b32 s8, v254, 4
	v_or_b32_e32 v2, s0, v97
	v_readlane_b32 s9, v254, 5
	s_lshl_b32 s8, s5, 2
	v_lshlrev_b64 v[4:5], 12, v[2:3]
	v_lshl_add_u64 v[32:33], v[72:73], 0, s[8:9]
	v_or_b32_e32 v8, 8, v2
	v_mov_b32_e32 v9, v3
	v_lshl_add_u64 v[4:5], v[32:33], 0, v[4:5]
	v_lshlrev_b64 v[8:9], 12, v[8:9]
	global_load_dwordx4 v[4:7], v[4:5], off nt
	v_lshl_add_u64 v[8:9], v[32:33], 0, v[8:9]
	v_or_b32_e32 v12, 16, v2
	v_mov_b32_e32 v13, v3
	global_load_dwordx4 v[8:11], v[8:9], off nt
	v_lshlrev_b64 v[12:13], 12, v[12:13]
	v_lshl_add_u64 v[12:13], v[32:33], 0, v[12:13]
	v_or_b32_e32 v16, 24, v2
	v_mov_b32_e32 v17, v3
	global_load_dwordx4 v[12:15], v[12:13], off nt
	v_lshlrev_b64 v[16:17], 12, v[16:17]
	v_lshl_add_u64 v[16:17], v[32:33], 0, v[16:17]
	v_or_b32_e32 v20, 32, v2
	v_mov_b32_e32 v21, v3
	global_load_dwordx4 v[16:19], v[16:17], off nt
	v_lshlrev_b64 v[20:21], 12, v[20:21]
	v_lshl_add_u64 v[20:21], v[32:33], 0, v[20:21]
	v_or_b32_e32 v24, 40, v2
	v_mov_b32_e32 v25, v3
	global_load_dwordx4 v[20:23], v[20:21], off nt
	v_lshlrev_b64 v[24:25], 12, v[24:25]
	v_lshl_add_u64 v[24:25], v[32:33], 0, v[24:25]
	v_or_b32_e32 v28, 48, v2
	v_mov_b32_e32 v29, v3
	global_load_dwordx4 v[24:27], v[24:25], off nt
	v_lshlrev_b64 v[28:29], 12, v[28:29]
	v_lshl_add_u64 v[28:29], v[32:33], 0, v[28:29]
	v_or_b32_e32 v2, 56, v2
	global_load_dwordx4 v[28:31], v[28:29], off nt
	v_lshlrev_b64 v[34:35], 12, v[2:3]
	v_lshl_add_u64 v[32:33], v[32:33], 0, v[34:35]
	global_load_dwordx4 v[32:35], v[32:33], off nt
	v_add_u32_e32 v2, v99, v105
	s_mov_b32 s1, s9
	v_writelane_b32 v254, s0, 4
	s_waitcnt vmcnt(7)
	ds_write2_b32 v2, v4, v5 offset1:1
	ds_write2_b32 v2, v6, v7 offset0:2 offset1:3
	v_add_u32_e32 v4, 0x420, v2
	v_writelane_b32 v254, s1, 5
	s_mov_b32 s1, s9
	s_waitcnt vmcnt(6)
	ds_write2_b32 v4, v8, v9 offset1:1
	v_add_u32_e32 v4, 0x428, v2
	ds_write2_b32 v4, v10, v11 offset1:1
	v_add_u32_e32 v4, 0x840, v2
	v_lshl_add_u64 v[8:9], s[0:1], 1, v[74:75]
	s_waitcnt vmcnt(5)
	ds_write2_b32 v4, v12, v13 offset1:1
	v_add_u32_e32 v4, 0x848, v2
	ds_write2_b32 v4, v14, v15 offset1:1
	v_add_u32_e32 v4, 0xc60, v2
	s_waitcnt vmcnt(4)
	ds_write2_b32 v4, v16, v17 offset1:1
	v_add_u32_e32 v4, 0xc68, v2
	ds_write2_b32 v4, v18, v19 offset1:1
	v_add_u32_e32 v4, 0x1080, v2
	s_waitcnt vmcnt(3)
	ds_write2_b32 v4, v20, v21 offset1:1
	v_add_u32_e32 v4, 0x1088, v2
	ds_write2_b32 v4, v22, v23 offset1:1
	v_add_u32_e32 v4, 0x14a0, v2
	s_waitcnt vmcnt(2)
	ds_write2_b32 v4, v24, v25 offset1:1
	v_add_u32_e32 v4, 0x14a8, v2
	ds_write2_b32 v4, v26, v27 offset1:1
	v_add_u32_e32 v4, 0x18c0, v2
	s_waitcnt vmcnt(1)
	ds_write2_b32 v4, v28, v29 offset1:1
	v_add_u32_e32 v4, 0x18c8, v2
	ds_write2_b32 v4, v30, v31 offset1:1
	v_add_u32_e32 v4, 0x1ce0, v2
	v_add_u32_e32 v2, 0x1ce8, v2
	s_waitcnt vmcnt(0)
	ds_write2_b32 v4, v32, v33 offset1:1
	ds_write2_b32 v2, v34, v35 offset1:1
	s_waitcnt lgkmcnt(0)
	ds_read2_b32 v[4:5], v103 offset1:33
	s_waitcnt lgkmcnt(0)
	v_cvt_pk_bf16_f32 v4, v4, v5
	ds_read2_b32 v[6:7], v103 offset0:66 offset1:99
	s_waitcnt lgkmcnt(0)
	v_cvt_pk_bf16_f32 v5, v6, v7
	ds_read2_b32 v[6:7], v103 offset0:132 offset1:165
	v_or_b32_e32 v2, s5, v97
	s_waitcnt lgkmcnt(0)
	v_cvt_pk_bf16_f32 v6, v6, v7
	ds_read2_b32 v[10:11], v103 offset0:198 offset1:231
	v_lshlrev_b32_e32 v2, 11, v2
	s_waitcnt lgkmcnt(0)
	v_cvt_pk_bf16_f32 v7, v10, v11
	v_lshl_add_u64 v[10:11], v[8:9], 0, v[2:3]
	global_store_dwordx4 v[10:11], v[4:7], off sc1
	ds_read2_b32 v[4:5], v103 offset0:8 offset1:41
	v_or_b32_e32 v2, s5, v107
	s_waitcnt lgkmcnt(0)
	v_cvt_pk_bf16_f32 v4, v4, v5
	ds_read2_b32 v[6:7], v103 offset0:74 offset1:107
	s_waitcnt lgkmcnt(0)
	v_cvt_pk_bf16_f32 v5, v6, v7
	ds_read2_b32 v[6:7], v103 offset0:140 offset1:173
	s_waitcnt lgkmcnt(0)
	v_cvt_pk_bf16_f32 v6, v6, v7
	ds_read2_b32 v[10:11], v103 offset0:206 offset1:239
	v_lshlrev_b32_e32 v2, 11, v2
	s_waitcnt lgkmcnt(0)
	v_cvt_pk_bf16_f32 v7, v10, v11
	v_lshl_add_u64 v[10:11], v[8:9], 0, v[2:3]
	global_store_dwordx4 v[10:11], v[4:7], off sc1
	ds_read2_b32 v[4:5], v103 offset0:16 offset1:49
	v_or_b32_e32 v2, s5, v109
	s_waitcnt lgkmcnt(0)
	v_cvt_pk_bf16_f32 v4, v4, v5
	ds_read2_b32 v[6:7], v103 offset0:82 offset1:115
	s_waitcnt lgkmcnt(0)
	v_cvt_pk_bf16_f32 v5, v6, v7
	ds_read2_b32 v[6:7], v103 offset0:148 offset1:181
	s_waitcnt lgkmcnt(0)
	v_cvt_pk_bf16_f32 v6, v6, v7
	ds_read2_b32 v[10:11], v103 offset0:214 offset1:247
	v_lshlrev_b32_e32 v2, 11, v2
	s_waitcnt lgkmcnt(0)
	v_cvt_pk_bf16_f32 v7, v10, v11
	v_lshl_add_u64 v[10:11], v[8:9], 0, v[2:3]
	global_store_dwordx4 v[10:11], v[4:7], off sc1
	ds_read2_b32 v[4:5], v103 offset0:24 offset1:57
	v_or_b32_e32 v2, s5, v112
	s_waitcnt lgkmcnt(0)
	v_cvt_pk_bf16_f32 v4, v4, v5
	ds_read2_b32 v[6:7], v103 offset0:90 offset1:123
	v_lshlrev_b32_e32 v2, 11, v2
	s_waitcnt lgkmcnt(0)
	v_cvt_pk_bf16_f32 v5, v6, v7
	ds_read2_b32 v[6:7], v103 offset0:156 offset1:189
	v_lshl_add_u64 v[8:9], v[8:9], 0, v[2:3]
	s_waitcnt lgkmcnt(0)
	v_cvt_pk_bf16_f32 v6, v6, v7
	ds_read2_b32 v[10:11], v103 offset0:222 offset1:255
	s_waitcnt lgkmcnt(0)
	v_cvt_pk_bf16_f32 v7, v10, v11
	global_store_dwordx4 v[8:9], v[4:7], off sc1
	s_waitcnt lgkmcnt(0)

; #define GAS __attribute__((address_space(1)))
; #define LAS __attribute__((address_space(3)))
; #define LDS_WAIT() asm volatile("s_waitcnt lgkmcnt(0)" ::: "memory")
; #define NTLOAD(p) __builtin_nontemporal_load(p)
; __device__ __forceinline__ void cv_item(const float* W, int N, const float* gk, bf16_t* WT, int ldt, int kofs, int drow, int kb, int nb, LAS float* scr, int lane) {
;     const int k0 = 64 * kb, n0 = 32 * nb, kq = lane >> 3, n4 = (lane & 7) * 4;
;     f32x4 v[8]; float sc[8];
; #pragma unroll
;     for (int i = 0; i < 8; ++i) { v[i] = NTLOAD((const GAS f32x4*)(W + (size_t)(k0 + 8 * i + kq) * N + n0 + n4)); sc[i] = gk ? gk[k0 + 8 * i + kq] : 1.0f; }
; #pragma unroll
;     for (int i = 0; i < 8; ++i) { LAS float* d = scr + (8 * i + kq) * 33 + n4; const f32x4 t = v[i] * sc[i]; d[0] = t[0]; d[1] = t[1]; d[2] = t[2]; d[3] = t[3]; }
;     LDS_WAIT(); asm volatile("" ::: "memory");
;     const int c = lane & 7;
; #pragma unroll
;     for (int j = 0; j < 4; ++j) { const int n = (lane >> 3) + 8 * j; const LAS float* s = scr + (8 * c) * 33 + n;
;         u32x4 o; o.x = pk2(s[0 * 33], s[1 * 33]); o.y = pk2(s[2 * 33], s[3 * 33]); o.z = pk2(s[4 * 33], s[5 * 33]); o.w = pk2(s[6 * 33], s[7 * 33]);
;         *(GAS u32x4*)(WT + (size_t)(drow + n) * ldt + kofs + k0 + 8 * c) = o; }
;     LDS_WAIT(); asm volatile("" ::: "memory");
; }
; __device__ __forceinline__ void cv_dispatch(const CvPtrs& P, unsigned char* ws, float* out, int layer, int r, LAS float* scr, int lane) {
;     ...
;     if (r < CI_A)  { const int nblk = D / 32, kb = r / nblk, nb = r % nblk; cv_item(P.w_a + (size_t)layer * DC * D, D, nullptr, WB + WB_WAB, D, 0, 32 * nb, kb, nb, scr, lane); return; } r -= CI_A;
;     if (r < CI_A)  { const int nblk = D / 32, kb = r / nblk, nb = r % nblk; cv_item(P.w_b + (size_t)layer * DSC * D, D, nullptr, WB + WB_WAB, D, DC, 32 * nb, kb, nb, scr, lane); return; } r -= CI_A;
;     if (r < CI_O)  { const int nblk = D / 32, kb = r / nblk, nb = r % nblk; cv_item(P.w_o + (size_t)layer * D * D, D, nullptr, WB + WB_WO, D, 0, 32 * nb, kb, nb, scr, lane); return; } r -= CI_O;
.LBB0_867:
	s_andn2_b64 vcc, exec, s[0:1]
	s_cbranch_vccnz .LBB0_869
	s_lshl_b32 s0, s4, 5
	s_and_b32 s5, s0, 0x3e0
	s_lshl_b32 s0, s4, 1
	s_and_b32 s0, s0, 0x1fc0
	s_addk_i32 s0, 0xee00
	v_readlane_b32 s8, v254, 4
	v_or_b32_e32 v2, s0, v97
	v_readlane_b32 s9, v254, 5
	s_lshl_b32 s8, s5, 2
	v_lshlrev_b64 v[4:5], 12, v[2:3]
	v_lshl_add_u64 v[32:33], v[76:77], 0, s[8:9]
	v_or_b32_e32 v8, 8, v2
	v_mov_b32_e32 v9, v3
	v_lshl_add_u64 v[4:5], v[32:33], 0, v[4:5]
	v_lshlrev_b64 v[8:9], 12, v[8:9]
	global_load_dwordx4 v[4:7], v[4:5], off nt
	v_lshl_add_u64 v[8:9], v[32:33], 0, v[8:9]
	v_or_b32_e32 v12, 16, v2
	v_mov_b32_e32 v13, v3
	global_load_dwordx4 v[8:11], v[8:9], off nt
	v_lshlrev_b64 v[12:13], 12, v[12:13]
	v_lshl_add_u64 v[12:13], v[32:33], 0, v[12:13]
	v_or_b32_e32 v16, 24, v2
	v_mov_b32_e32 v17, v3
	global_load_dwordx4 v[12:15], v[12:13], off nt
	v_lshlrev_b64 v[16:17], 12, v[16:17]
	v_lshl_add_u64 v[16:17], v[32:33], 0, v[16:17]
	v_or_b32_e32 v20, 32, v2
	v_mov_b32_e32 v21, v3
	global_load_dwordx4 v[16:19], v[16:17], off nt
	v_lshlrev_b64 v[20:21], 12, v[20:21]
	v_lshl_add_u64 v[20:21], v[32:33], 0, v[20:21]
	v_or_b32_e32 v24, 40, v2
	v_mov_b32_e32 v25, v3
	global_load_dwordx4 v[20:23], v[20:21], off nt
	v_lshlrev_b64 v[24:25], 12, v[24:25]
	v_lshl_add_u64 v[24:25], v[32:33], 0, v[24:25]
	v_or_b32_e32 v28, 48, v2
	v_mov_b32_e32 v29, v3
	global_load_dwordx4 v[24:27], v[24:25], off nt
	v_lshlrev_b64 v[28:29], 12, v[28:29]
	v_lshl_add_u64 v[28:29], v[32:33], 0, v[28:29]
	v_or_b32_e32 v2, 56, v2
	global_load_dwordx4 v[28:31], v[28:29], off nt
	v_lshlrev_b64 v[34:35], 12, v[2:3]
	v_lshl_add_u64 v[32:33], v[32:33], 0, v[34:35]
	global_load_dwordx4 v[32:35], v[32:33], off nt
	v_add_u32_e32 v2, v99, v105
	s_mov_b32 s1, s9
	v_writelane_b32 v254, s0, 4
	s_waitcnt vmcnt(7)
	ds_write2_b32 v2, v4, v5 offset1:1
	ds_write2_b32 v2, v6, v7 offset0:2 offset1:3
	v_add_u32_e32 v4, 0x420, v2
	v_writelane_b32 v254, s1, 5
	s_mov_b32 s1, s9
	s_waitcnt vmcnt(6)
	ds_write2_b32 v4, v8, v9 offset1:1
	v_add_u32_e32 v4, 0x428, v2
	ds_write2_b32 v4, v10, v11 offset1:1
	v_add_u32_e32 v4, 0x840, v2
	v_lshl_add_u64 v[8:9], s[0:1], 1, v[78:79]
	s_waitcnt vmcnt(5)
	ds_write2_b32 v4, v12, v13 offset1:1
	v_add_u32_e32 v4, 0x848, v2
	ds_write2_b32 v4, v14, v15 offset1:1
	v_add_u32_e32 v4, 0xc60, v2
	s_waitcnt vmcnt(4)
	ds_write2_b32 v4, v16, v17 offset1:1
	v_add_u32_e32 v4, 0xc68, v2
	ds_write2_b32 v4, v18, v19 offset1:1
	v_add_u32_e32 v4, 0x1080, v2
	s_waitcnt vmcnt(3)
	ds_write2_b32 v4, v20, v21 offset1:1
	v_add_u32_e32 v4, 0x1088, v2
	ds_write2_b32 v4, v22, v23 offset1:1
	v_add_u32_e32 v4, 0x14a0, v2
	s_waitcnt vmcnt(2)
	ds_write2_b32 v4, v24, v25 offset1:1
	v_add_u32_e32 v4, 0x14a8, v2
	ds_write2_b32 v4, v26, v27 offset1:1
	v_add_u32_e32 v4, 0x18c0, v2
	s_waitcnt vmcnt(1)
	ds_write2_b32 v4, v28, v29 offset1:1
	v_add_u32_e32 v4, 0x18c8, v2
	ds_write2_b32 v4, v30, v31 offset1:1
	v_add_u32_e32 v4, 0x1ce0, v2
	v_add_u32_e32 v2, 0x1ce8, v2
	s_waitcnt vmcnt(0)
	ds_write2_b32 v4, v32, v33 offset1:1
	ds_write2_b32 v2, v34, v35 offset1:1
	s_waitcnt lgkmcnt(0)
	ds_read2_b32 v[4:5], v103 offset1:33
	s_waitcnt lgkmcnt(0)
	v_cvt_pk_bf16_f32 v4, v4, v5
	ds_read2_b32 v[6:7], v103 offset0:66 offset1:99
	s_waitcnt lgkmcnt(0)
	v_cvt_pk_bf16_f32 v5, v6, v7
	ds_read2_b32 v[6:7], v103 offset0:132 offset1:165
	v_or_b32_e32 v2, s5, v97
	s_waitcnt lgkmcnt(0)
	v_cvt_pk_bf16_f32 v6, v6, v7
	ds_read2_b32 v[10:11], v103 offset0:198 offset1:231
	v_lshlrev_b32_e32 v2, 11, v2
	s_waitcnt lgkmcnt(0)
	v_cvt_pk_bf16_f32 v7, v10, v11
	v_lshl_add_u64 v[10:11], v[8:9], 0, v[2:3]
	global_store_dwordx4 v[10:11], v[4:7], off sc1
	ds_read2_b32 v[4:5], v103 offset0:8 offset1:41
	v_or_b32_e32 v2, s5, v107
	s_waitcnt lgkmcnt(0)
	v_cvt_pk_bf16_f32 v4, v4, v5
	ds_read2_b32 v[6:7], v103 offset0:74 offset1:107
	s_waitcnt lgkmcnt(0)
	v_cvt_pk_bf16_f32 v5, v6, v7
	ds_read2_b32 v[6:7], v103 offset0:140 offset1:173
	s_waitcnt lgkmcnt(0)
	v_cvt_pk_bf16_f32 v6, v6, v7
	ds_read2_b32 v[10:11], v103 offset0:206 offset1:239
	v_lshlrev_b32_e32 v2, 11, v2
	s_waitcnt lgkmcnt(0)
	v_cvt_pk_bf16_f32 v7, v10, v11
	v_lshl_add_u64 v[10:11], v[8:9], 0, v[2:3]
	global_store_dwordx4 v[10:11], v[4:7], off sc1
	ds_read2_b32 v[4:5], v103 offset0:16 offset1:49
	v_or_b32_e32 v2, s5, v109
	s_waitcnt lgkmcnt(0)
	v_cvt_pk_bf16_f32 v4, v4, v5
	ds_read2_b32 v[6:7], v103 offset0:82 offset1:115
	s_waitcnt lgkmcnt(0)
	v_cvt_pk_bf16_f32 v5, v6, v7
	ds_read2_b32 v[6:7], v103 offset0:148 offset1:181
	s_waitcnt lgkmcnt(0)
	v_cvt_pk_bf16_f32 v6, v6, v7
	ds_read2_b32 v[10:11], v103 offset0:214 offset1:247
	v_lshlrev_b32_e32 v2, 11, v2
	s_waitcnt lgkmcnt(0)
	v_cvt_pk_bf16_f32 v7, v10, v11
	v_lshl_add_u64 v[10:11], v[8:9], 0, v[2:3]
	global_store_dwordx4 v[10:11], v[4:7], off sc1
	ds_read2_b32 v[4:5], v103 offset0:24 offset1:57
	v_or_b32_e32 v2, s5, v112
	s_waitcnt lgkmcnt(0)
	v_cvt_pk_bf16_f32 v4, v4, v5
	ds_read2_b32 v[6:7], v103 offset0:90 offset1:123
	v_lshlrev_b32_e32 v2, 11, v2
	s_waitcnt lgkmcnt(0)
	v_cvt_pk_bf16_f32 v5, v6, v7
	ds_read2_b32 v[6:7], v103 offset0:156 offset1:189
	v_lshl_add_u64 v[8:9], v[8:9], 0, v[2:3]
	s_waitcnt lgkmcnt(0)
	v_cvt_pk_bf16_f32 v6, v6, v7
	ds_read2_b32 v[10:11], v103 offset0:222 offset1:255
	s_waitcnt lgkmcnt(0)
	v_cvt_pk_bf16_f32 v7, v10, v11
	global_store_dwordx4 v[8:9], v[4:7], off sc1
	s_waitcnt lgkmcnt(0)

; #define GAS __attribute__((address_space(1)))
; #define LAS __attribute__((address_space(3)))
; #define LDS_WAIT() asm volatile("s_waitcnt lgkmcnt(0)" ::: "memory")
; #define NTLOAD(p) __builtin_nontemporal_load(p)
; __device__ __forceinline__ void cv_item(const float* W, int N, const float* gk, bf16_t* WT, int ldt, int kofs, int drow, int kb, int nb, LAS float* scr, int lane) {
;     const int k0 = 64 * kb, n0 = 32 * nb, kq = lane >> 3, n4 = (lane & 7) * 4;
;     f32x4 v[8]; float sc[8];
; #pragma unroll
;     for (int i = 0; i < 8; ++i) { v[i] = NTLOAD((const GAS f32x4*)(W + (size_t)(k0 + 8 * i + kq) * N + n0 + n4)); sc[i] = gk ? gk[k0 + 8 * i + kq] : 1.0f; }
; #pragma unroll
;     for (int i = 0; i < 8; ++i) { LAS float* d = scr + (8 * i + kq) * 33 + n4; const f32x4 t = v[i] * sc[i]; d[0] = t[0]; d[1] = t[1]; d[2] = t[2]; d[3] = t[3]; }
;     LDS_WAIT(); asm volatile("" ::: "memory");
;     const int c = lane & 7;
; #pragma unroll
;     for (int j = 0; j < 4; ++j) { const int n = (lane >> 3) + 8 * j; const LAS float* s = scr + (8 * c) * 33 + n;
;         u32x4 o; o.x = pk2(s[0 * 33], s[1 * 33]); o.y = pk2(s[2 * 33], s[3 * 33]); o.z = pk2(s[4 * 33], s[5 * 33]); o.w = pk2(s[6 * 33], s[7 * 33]);
;         *(GAS u32x4*)(WT + (size_t)(drow + n) * ldt + kofs + k0 + 8 * c) = o; }
;     LDS_WAIT(); asm volatile("" ::: "memory");
; }
.LBB0_911:
	s_waitcnt vmcnt(7)
	v_pk_mul_f32 v[6:7], v[6:7], v[96:97] op_sel_hi:[1,0]
	v_pk_mul_f32 v[4:5], v[4:5], v[96:97] op_sel_hi:[1,0]
	v_add_u32_e32 v96, v99, v105
	ds_write2_b32 v96, v4, v5 offset1:1
	ds_write2_b32 v96, v6, v7 offset0:2 offset1:3
	s_waitcnt vmcnt(6)
	v_pk_mul_f32 v[4:5], v[10:11], v[2:3] op_sel_hi:[1,0]
	v_pk_mul_f32 v[6:7], v[8:9], v[2:3] op_sel_hi:[1,0]
	v_add_u32_e32 v2, 0x420, v96
	ds_write2_b32 v2, v6, v7 offset1:1
	v_add_u32_e32 v2, 0x428, v96
	ds_write2_b32 v2, v4, v5 offset1:1
	s_waitcnt vmcnt(5)
	v_pk_mul_f32 v[6:7], v[12:13], v[100:101] op_sel_hi:[1,0]
	v_add_u32_e32 v2, 0x840, v96
	v_pk_mul_f32 v[4:5], v[14:15], v[100:101] op_sel_hi:[1,0]
	ds_write2_b32 v2, v6, v7 offset1:1
	v_add_u32_e32 v2, 0x848, v96
	ds_write2_b32 v2, v4, v5 offset1:1
	s_waitcnt vmcnt(4)
	v_pk_mul_f32 v[6:7], v[16:17], v[98:99] op_sel_hi:[1,0]
	v_add_u32_e32 v2, 0xc60, v96
	v_pk_mul_f32 v[4:5], v[18:19], v[98:99] op_sel_hi:[1,0]
	ds_write2_b32 v2, v6, v7 offset1:1
	v_add_u32_e32 v2, 0xc68, v96
	ds_write2_b32 v2, v4, v5 offset1:1
	s_waitcnt vmcnt(3)
	v_pk_mul_f32 v[6:7], v[20:21], v[104:105] op_sel_hi:[1,0]
	v_add_u32_e32 v2, 0x1080, v96
	v_pk_mul_f32 v[4:5], v[22:23], v[104:105] op_sel_hi:[1,0]
	ds_write2_b32 v2, v6, v7 offset1:1
	v_add_u32_e32 v2, 0x1088, v96
	ds_write2_b32 v2, v4, v5 offset1:1
	s_waitcnt vmcnt(2)
	v_pk_mul_f32 v[6:7], v[24:25], v[102:103] op_sel_hi:[1,0]
	v_add_u32_e32 v2, 0x14a0, v96
	v_pk_mul_f32 v[4:5], v[26:27], v[102:103] op_sel_hi:[1,0]
	ds_write2_b32 v2, v6, v7 offset1:1
	v_add_u32_e32 v2, 0x14a8, v96
	ds_write2_b32 v2, v4, v5 offset1:1
	s_waitcnt vmcnt(1)
	v_pk_mul_f32 v[6:7], v[28:29], v[108:109] op_sel_hi:[1,0]
	v_add_u32_e32 v2, 0x18c0, v96
	v_pk_mul_f32 v[4:5], v[30:31], v[108:109] op_sel_hi:[1,0]
	ds_write2_b32 v2, v6, v7 offset1:1
	v_add_u32_e32 v2, 0x18c8, v96
	ds_write2_b32 v2, v4, v5 offset1:1
	s_waitcnt vmcnt(0)
	v_pk_mul_f32 v[6:7], v[32:33], v[106:107] op_sel_hi:[1,0]
	v_add_u32_e32 v2, 0x1ce0, v96
	v_pk_mul_f32 v[4:5], v[34:35], v[106:107] op_sel_hi:[1,0]
	ds_write2_b32 v2, v6, v7 offset1:1
	v_add_u32_e32 v2, 0x1ce8, v96
	ds_write2_b32 v2, v4, v5 offset1:1
	s_waitcnt lgkmcnt(0)
	ds_read2_b32 v[4:5], v103 offset1:33
	s_waitcnt lgkmcnt(0)
	v_cvt_pk_bf16_f32 v4, v4, v5
	ds_read2_b32 v[6:7], v103 offset0:66 offset1:99
	s_waitcnt lgkmcnt(0)
	v_cvt_pk_bf16_f32 v5, v6, v7
	ds_read2_b32 v[6:7], v103 offset0:132 offset1:165
	s_waitcnt lgkmcnt(0)
	v_cvt_pk_bf16_f32 v6, v6, v7
	ds_read2_b32 v[8:9], v103 offset0:198 offset1:231
	s_and_b32 s0, 0xffff, s5
	s_waitcnt lgkmcnt(0)
	v_cvt_pk_bf16_f32 v7, v8, v9
	v_add_u32_e32 v8, s4, v97
	s_lshl_b32 s12, s0, 1
	v_ashrrev_i32_e32 v9, 31, v8
	v_lshl_add_u64 v[10:11], v[36:37], 0, s[12:13]
	v_lshlrev_b64 v[8:9], 11, v[8:9]
	v_lshl_add_u64 v[8:9], v[10:11], 0, v[8:9]
	ds_read2_b32 v[12:13], v103 offset0:8 offset1:41
	global_store_dwordx4 v[8:9], v[4:7], off sc1
	s_mov_b32 s1, s13
	v_writelane_b32 v254, s0, 4
	s_waitcnt lgkmcnt(0)
	v_cvt_pk_bf16_f32 v4, v12, v13
	ds_read2_b32 v[6:7], v103 offset0:74 offset1:107
	s_waitcnt lgkmcnt(0)
	v_cvt_pk_bf16_f32 v5, v6, v7
	ds_read2_b32 v[6:7], v103 offset0:140 offset1:173
	s_waitcnt lgkmcnt(0)
	v_cvt_pk_bf16_f32 v6, v6, v7
	ds_read2_b32 v[8:9], v103 offset0:206 offset1:239
	s_waitcnt lgkmcnt(0)
	v_cvt_pk_bf16_f32 v7, v8, v9
	v_add_u32_e32 v8, s4, v107
	v_ashrrev_i32_e32 v9, 31, v8
	v_lshlrev_b64 v[8:9], 11, v[8:9]
	v_lshl_add_u64 v[8:9], v[10:11], 0, v[8:9]
	ds_read2_b32 v[12:13], v103 offset0:16 offset1:49
	global_store_dwordx4 v[8:9], v[4:7], off sc1
	v_writelane_b32 v254, s1, 5
	s_waitcnt lgkmcnt(0)
	v_cvt_pk_bf16_f32 v4, v12, v13
	ds_read2_b32 v[6:7], v103 offset0:82 offset1:115
	s_waitcnt lgkmcnt(0)
	v_cvt_pk_bf16_f32 v5, v6, v7
	ds_read2_b32 v[6:7], v103 offset0:148 offset1:181
	s_waitcnt lgkmcnt(0)
	v_cvt_pk_bf16_f32 v6, v6, v7
	ds_read2_b32 v[8:9], v103 offset0:214 offset1:247
	s_waitcnt lgkmcnt(0)
	v_cvt_pk_bf16_f32 v7, v8, v9
	v_add_u32_e32 v8, s4, v109
	v_ashrrev_i32_e32 v9, 31, v8
	v_lshlrev_b64 v[8:9], 11, v[8:9]
	v_lshl_add_u64 v[8:9], v[10:11], 0, v[8:9]
	ds_read2_b32 v[12:13], v103 offset0:24 offset1:57
	global_store_dwordx4 v[8:9], v[4:7], off sc1
	s_waitcnt lgkmcnt(0)
	s_nop 0
	v_cvt_pk_bf16_f32 v4, v12, v13
	ds_read2_b32 v[6:7], v103 offset0:90 offset1:123
	s_waitcnt lgkmcnt(0)
	v_cvt_pk_bf16_f32 v5, v6, v7
	ds_read2_b32 v[6:7], v103 offset0:156 offset1:189
	s_waitcnt lgkmcnt(0)
	v_cvt_pk_bf16_f32 v6, v6, v7
	ds_read2_b32 v[8:9], v103 offset0:222 offset1:255
	s_waitcnt lgkmcnt(0)
	v_cvt_pk_bf16_f32 v7, v8, v9
	v_add_u32_e32 v8, s4, v112
	v_ashrrev_i32_e32 v9, 31, v8
	v_lshlrev_b64 v[8:9], 11, v[8:9]
	v_lshl_add_u64 v[8:9], v[10:11], 0, v[8:9]
	global_store_dwordx4 v[8:9], v[4:7], off sc1
	s_waitcnt lgkmcnt(0)

; #define GAS __attribute__((address_space(1)))
; #define LAS __attribute__((address_space(3)))
; #define LDS_WAIT() asm volatile("s_waitcnt lgkmcnt(0)" ::: "memory")
; #define NTLOAD(p) __builtin_nontemporal_load(p)
; __device__ __forceinline__ void cv_item(const float* W, int N, const float* gk, bf16_t* WT, int ldt, int kofs, int drow, int kb, int nb, LAS float* scr, int lane) {
;     const int k0 = 64 * kb, n0 = 32 * nb, kq = lane >> 3, n4 = (lane & 7) * 4;
;     f32x4 v[8]; float sc[8];
; #pragma unroll
;     for (int i = 0; i < 8; ++i) { v[i] = NTLOAD((const GAS f32x4*)(W + (size_t)(k0 + 8 * i + kq) * N + n0 + n4)); sc[i] = gk ? gk[k0 + 8 * i + kq] : 1.0f; }
; #pragma unroll
;     for (int i = 0; i < 8; ++i) { LAS float* d = scr + (8 * i + kq) * 33 + n4; const f32x4 t = v[i] * sc[i]; d[0] = t[0]; d[1] = t[1]; d[2] = t[2]; d[3] = t[3]; }
;     LDS_WAIT(); asm volatile("" ::: "memory");
;     const int c = lane & 7;
; #pragma unroll
;     for (int j = 0; j < 4; ++j) { const int n = (lane >> 3) + 8 * j; const LAS float* s = scr + (8 * c) * 33 + n;
;         u32x4 o; o.x = pk2(s[0 * 33], s[1 * 33]); o.y = pk2(s[2 * 33], s[3 * 33]); o.z = pk2(s[4 * 33], s[5 * 33]); o.w = pk2(s[6 * 33], s[7 * 33]);
;         *(GAS u32x4*)(WT + (size_t)(drow + n) * ldt + kofs + k0 + 8 * c) = o; }
;     LDS_WAIT(); asm volatile("" ::: "memory");
; }
.LBB0_931:
	s_waitcnt vmcnt(7)
	v_pk_mul_f32 v[6:7], v[6:7], v[96:97] op_sel_hi:[1,0]
	v_pk_mul_f32 v[4:5], v[4:5], v[96:97] op_sel_hi:[1,0]
	v_add_u32_e32 v96, v99, v105
	ds_write2_b32 v96, v4, v5 offset1:1
	ds_write2_b32 v96, v6, v7 offset0:2 offset1:3
	s_waitcnt vmcnt(6)
	v_pk_mul_f32 v[4:5], v[10:11], v[2:3] op_sel_hi:[1,0]
	v_pk_mul_f32 v[6:7], v[8:9], v[2:3] op_sel_hi:[1,0]
	v_add_u32_e32 v2, 0x420, v96
	ds_write2_b32 v2, v6, v7 offset1:1
	v_add_u32_e32 v2, 0x428, v96
	ds_write2_b32 v2, v4, v5 offset1:1
	s_waitcnt vmcnt(5)
	v_pk_mul_f32 v[6:7], v[12:13], v[100:101] op_sel_hi:[1,0]
	v_add_u32_e32 v2, 0x840, v96
	v_pk_mul_f32 v[4:5], v[14:15], v[100:101] op_sel_hi:[1,0]
	ds_write2_b32 v2, v6, v7 offset1:1
	v_add_u32_e32 v2, 0x848, v96
	ds_write2_b32 v2, v4, v5 offset1:1
	s_waitcnt vmcnt(4)
	v_pk_mul_f32 v[6:7], v[16:17], v[98:99] op_sel_hi:[1,0]
	v_add_u32_e32 v2, 0xc60, v96
	v_pk_mul_f32 v[4:5], v[18:19], v[98:99] op_sel_hi:[1,0]
	ds_write2_b32 v2, v6, v7 offset1:1
	v_add_u32_e32 v2, 0xc68, v96
	ds_write2_b32 v2, v4, v5 offset1:1
	s_waitcnt vmcnt(3)
	v_pk_mul_f32 v[6:7], v[20:21], v[104:105] op_sel_hi:[1,0]
	v_add_u32_e32 v2, 0x1080, v96
	v_pk_mul_f32 v[4:5], v[22:23], v[104:105] op_sel_hi:[1,0]
	ds_write2_b32 v2, v6, v7 offset1:1
	v_add_u32_e32 v2, 0x1088, v96
	ds_write2_b32 v2, v4, v5 offset1:1
	s_waitcnt vmcnt(2)
	v_pk_mul_f32 v[6:7], v[24:25], v[102:103] op_sel_hi:[1,0]
	v_add_u32_e32 v2, 0x14a0, v96
	v_pk_mul_f32 v[4:5], v[26:27], v[102:103] op_sel_hi:[1,0]
	ds_write2_b32 v2, v6, v7 offset1:1
	v_add_u32_e32 v2, 0x14a8, v96
	ds_write2_b32 v2, v4, v5 offset1:1
	s_waitcnt vmcnt(1)
	v_pk_mul_f32 v[6:7], v[28:29], v[108:109] op_sel_hi:[1,0]
	v_add_u32_e32 v2, 0x18c0, v96
	v_pk_mul_f32 v[4:5], v[30:31], v[108:109] op_sel_hi:[1,0]
	ds_write2_b32 v2, v6, v7 offset1:1
	v_add_u32_e32 v2, 0x18c8, v96
	ds_write2_b32 v2, v4, v5 offset1:1
	s_waitcnt vmcnt(0)
	v_pk_mul_f32 v[6:7], v[32:33], v[106:107] op_sel_hi:[1,0]
	v_add_u32_e32 v2, 0x1ce0, v96
	v_pk_mul_f32 v[4:5], v[34:35], v[106:107] op_sel_hi:[1,0]
	ds_write2_b32 v2, v6, v7 offset1:1
	v_add_u32_e32 v2, 0x1ce8, v96
	ds_write2_b32 v2, v4, v5 offset1:1
	s_waitcnt lgkmcnt(0)
	v_readlane_b32 s8, v254, 4
	ds_read2_b32 v[4:5], v103 offset1:33
	v_readlane_b32 s9, v254, 5
	s_waitcnt lgkmcnt(0)
	v_cvt_pk_bf16_f32 v4, v4, v5
	ds_read2_b32 v[6:7], v103 offset0:66 offset1:99
	s_mov_b32 s1, s9
	v_or_b32_e32 v2, s4, v97
	s_waitcnt lgkmcnt(0)
	v_cvt_pk_bf16_f32 v5, v6, v7
	ds_read2_b32 v[6:7], v103 offset0:132 offset1:165
	v_lshl_add_u64 v[10:11], s[0:1], 1, v[58:59]
	v_lshlrev_b32_e32 v2, 11, v2
	s_waitcnt lgkmcnt(0)
	v_cvt_pk_bf16_f32 v6, v6, v7
	ds_read2_b32 v[8:9], v103 offset0:198 offset1:231
	s_waitcnt lgkmcnt(0)
	v_cvt_pk_bf16_f32 v7, v8, v9
	v_lshl_add_u64 v[12:13], v[10:11], 0, v[2:3]
	ds_read2_b32 v[8:9], v103 offset0:8 offset1:41
	global_store_dwordx4 v[12:13], v[4:7], off sc1
	v_or_b32_e32 v2, s4, v107
	v_lshlrev_b32_e32 v2, 11, v2
	s_waitcnt lgkmcnt(0)
	v_cvt_pk_bf16_f32 v4, v8, v9
	ds_read2_b32 v[6:7], v103 offset0:74 offset1:107
	s_waitcnt lgkmcnt(0)
	v_cvt_pk_bf16_f32 v5, v6, v7
	ds_read2_b32 v[6:7], v103 offset0:140 offset1:173
	s_waitcnt lgkmcnt(0)
	v_cvt_pk_bf16_f32 v6, v6, v7
	ds_read2_b32 v[8:9], v103 offset0:206 offset1:239
	s_waitcnt lgkmcnt(0)
	v_cvt_pk_bf16_f32 v7, v8, v9
	v_lshl_add_u64 v[12:13], v[10:11], 0, v[2:3]
	ds_read2_b32 v[8:9], v103 offset0:16 offset1:49
	global_store_dwordx4 v[12:13], v[4:7], off sc1
	v_or_b32_e32 v2, s4, v109
	v_lshlrev_b32_e32 v2, 11, v2
	s_waitcnt lgkmcnt(0)
	v_cvt_pk_bf16_f32 v4, v8, v9
	ds_read2_b32 v[6:7], v103 offset0:82 offset1:115
	s_waitcnt lgkmcnt(0)
	v_cvt_pk_bf16_f32 v5, v6, v7
	ds_read2_b32 v[6:7], v103 offset0:148 offset1:181
	s_waitcnt lgkmcnt(0)
	v_cvt_pk_bf16_f32 v6, v6, v7
	ds_read2_b32 v[8:9], v103 offset0:214 offset1:247
	s_waitcnt lgkmcnt(0)
	v_cvt_pk_bf16_f32 v7, v8, v9
	v_lshl_add_u64 v[12:13], v[10:11], 0, v[2:3]
	ds_read2_b32 v[8:9], v103 offset0:24 offset1:57
	global_store_dwordx4 v[12:13], v[4:7], off sc1
	v_or_b32_e32 v2, s4, v112
	v_lshlrev_b32_e32 v2, 11, v2
	s_waitcnt lgkmcnt(0)
	v_cvt_pk_bf16_f32 v4, v8, v9
	ds_read2_b32 v[6:7], v103 offset0:90 offset1:123
	s_waitcnt lgkmcnt(0)
	v_cvt_pk_bf16_f32 v5, v6, v7
	ds_read2_b32 v[6:7], v103 offset0:156 offset1:189
	s_waitcnt lgkmcnt(0)
	v_cvt_pk_bf16_f32 v6, v6, v7
	ds_read2_b32 v[8:9], v103 offset0:222 offset1:255
	s_waitcnt lgkmcnt(0)
	v_cvt_pk_bf16_f32 v7, v8, v9
	v_lshl_add_u64 v[8:9], v[10:11], 0, v[2:3]
	global_store_dwordx4 v[8:9], v[4:7], off sc1
	s_waitcnt lgkmcnt(0)
	s_mov_b64 s[0:1], 0
; #define GAS __attribute__((address_space(1)))
; #define LAS __attribute__((address_space(3)))
; #define LDS_WAIT() asm volatile("s_waitcnt lgkmcnt(0)" ::: "memory")
; #define NTLOAD(p) __builtin_nontemporal_load(p)
; __device__ __forceinline__ void cv_item(const float* W, int N, const float* gk, bf16_t* WT, int ldt, int kofs, int drow, int kb, int nb, LAS float* scr, int lane) {
;     const int k0 = 64 * kb, n0 = 32 * nb, kq = lane >> 3, n4 = (lane & 7) * 4;
;     f32x4 v[8]; float sc[8];
; #pragma unroll
;     for (int i = 0; i < 8; ++i) { v[i] = NTLOAD((const GAS f32x4*)(W + (size_t)(k0 + 8 * i + kq) * N + n0 + n4)); sc[i] = gk ? gk[k0 + 8 * i + kq] : 1.0f; }
; #pragma unroll
;     for (int i = 0; i < 8; ++i) { LAS float* d = scr + (8 * i + kq) * 33 + n4; const f32x4 t = v[i] * sc[i]; d[0] = t[0]; d[1] = t[1]; d[2] = t[2]; d[3] = t[3]; }
;     LDS_WAIT(); asm volatile("" ::: "memory");
;     const int c = lane & 7;
; #pragma unroll
;     for (int j = 0; j < 4; ++j) { const int n = (lane >> 3) + 8 * j; const LAS float* s = scr + (8 * c) * 33 + n;
;         u32x4 o; o.x = pk2(s[0 * 33], s[1 * 33]); o.y = pk2(s[2 * 33], s[3 * 33]); o.z = pk2(s[4 * 33], s[5 * 33]); o.w = pk2(s[6 * 33], s[7 * 33]);
;         *(GAS u32x4*)(WT + (size_t)(drow + n) * ldt + kofs + k0 + 8 * c) = o; }
;     LDS_WAIT(); asm volatile("" ::: "memory");
; }
; __device__ __forceinline__ void cv_dispatch(const CvPtrs& P, unsigned char* ws, float* out, int layer, int r, LAS float* scr, int lane) {
;     ...
;     if (r < CI_DN) { const int nblk = D / 32, kb = r / nblk, nb = r % nblk; cv_item(P.w_dn + (size_t)layer * DFF * D, D, nullptr, WB0 + WB_WDN, DFF, 0, 32 * nb, kb, nb, scr, lane); return; } r -= CI_DN;
.LBB0_932:
	s_and_b64 vcc, exec, s[0:1]
	s_cbranch_vccz .LBB0_934
	s_add_i32 s0, s5, 0xffffd000
	v_readlane_b32 s8, v254, 4
	v_or_b32_e32 v2, s0, v97
	v_readlane_b32 s9, v254, 5
	s_lshl_b32 s8, s4, 2
	v_lshlrev_b64 v[4:5], 12, v[2:3]
	v_lshl_add_u64 v[32:33], v[40:41], 0, s[8:9]
	v_or_b32_e32 v8, 8, v2
	v_mov_b32_e32 v9, v3
	v_lshl_add_u64 v[4:5], v[32:33], 0, v[4:5]
	v_lshlrev_b64 v[8:9], 12, v[8:9]
	global_load_dwordx4 v[4:7], v[4:5], off nt
	v_lshl_add_u64 v[8:9], v[32:33], 0, v[8:9]
	v_or_b32_e32 v12, 16, v2
	v_mov_b32_e32 v13, v3
	global_load_dwordx4 v[8:11], v[8:9], off nt
	v_lshlrev_b64 v[12:13], 12, v[12:13]
	v_lshl_add_u64 v[12:13], v[32:33], 0, v[12:13]
	v_or_b32_e32 v16, 24, v2
	v_mov_b32_e32 v17, v3
	global_load_dwordx4 v[12:15], v[12:13], off nt
	v_lshlrev_b64 v[16:17], 12, v[16:17]
	v_lshl_add_u64 v[16:17], v[32:33], 0, v[16:17]
	v_or_b32_e32 v20, 32, v2
	v_mov_b32_e32 v21, v3
	global_load_dwordx4 v[16:19], v[16:17], off nt
	v_lshlrev_b64 v[20:21], 12, v[20:21]
	v_lshl_add_u64 v[20:21], v[32:33], 0, v[20:21]
	v_or_b32_e32 v24, 40, v2
	v_mov_b32_e32 v25, v3
	global_load_dwordx4 v[20:23], v[20:21], off nt
	v_lshlrev_b64 v[24:25], 12, v[24:25]
	v_lshl_add_u64 v[24:25], v[32:33], 0, v[24:25]
	v_or_b32_e32 v28, 48, v2
	v_mov_b32_e32 v29, v3
	global_load_dwordx4 v[24:27], v[24:25], off nt
	v_lshlrev_b64 v[28:29], 12, v[28:29]
	v_lshl_add_u64 v[28:29], v[32:33], 0, v[28:29]
	v_or_b32_e32 v2, 56, v2
	global_load_dwordx4 v[28:31], v[28:29], off nt
	v_lshlrev_b64 v[34:35], 12, v[2:3]
	v_lshl_add_u64 v[32:33], v[32:33], 0, v[34:35]
	global_load_dwordx4 v[32:35], v[32:33], off nt
	v_add_u32_e32 v2, v99, v105
	s_mov_b32 s1, s9
	v_writelane_b32 v254, s0, 4
	s_waitcnt vmcnt(7)
	ds_write2_b32 v2, v4, v5 offset1:1
	ds_write2_b32 v2, v6, v7 offset0:2 offset1:3
	v_add_u32_e32 v4, 0x420, v2
	v_writelane_b32 v254, s1, 5
	s_mov_b32 s1, s9
	s_waitcnt vmcnt(6)
	ds_write2_b32 v4, v8, v9 offset1:1
	v_add_u32_e32 v4, 0x428, v2
	ds_write2_b32 v4, v10, v11 offset1:1
	v_add_u32_e32 v4, 0x840, v2
	v_lshl_add_u64 v[8:9], s[0:1], 1, v[62:63]
	s_waitcnt vmcnt(5)
	ds_write2_b32 v4, v12, v13 offset1:1
	v_add_u32_e32 v4, 0x848, v2
	ds_write2_b32 v4, v14, v15 offset1:1
	v_add_u32_e32 v4, 0xc60, v2
	s_waitcnt vmcnt(4)
	ds_write2_b32 v4, v16, v17 offset1:1
	v_add_u32_e32 v4, 0xc68, v2
	ds_write2_b32 v4, v18, v19 offset1:1
	v_add_u32_e32 v4, 0x1080, v2
	s_waitcnt vmcnt(3)
	ds_write2_b32 v4, v20, v21 offset1:1
	v_add_u32_e32 v4, 0x1088, v2
	ds_write2_b32 v4, v22, v23 offset1:1
	v_add_u32_e32 v4, 0x14a0, v2
	s_waitcnt vmcnt(2)
	ds_write2_b32 v4, v24, v25 offset1:1
	v_add_u32_e32 v4, 0x14a8, v2
	ds_write2_b32 v4, v26, v27 offset1:1
	v_add_u32_e32 v4, 0x18c0, v2
	s_waitcnt vmcnt(1)
	ds_write2_b32 v4, v28, v29 offset1:1
	v_add_u32_e32 v4, 0x18c8, v2
	ds_write2_b32 v4, v30, v31 offset1:1
	v_add_u32_e32 v4, 0x1ce0, v2
	v_add_u32_e32 v2, 0x1ce8, v2
	s_waitcnt vmcnt(0)
	ds_write2_b32 v4, v32, v33 offset1:1
	ds_write2_b32 v2, v34, v35 offset1:1
	s_waitcnt lgkmcnt(0)
	ds_read2_b32 v[4:5], v103 offset1:33
	s_waitcnt lgkmcnt(0)
	v_cvt_pk_bf16_f32 v4, v4, v5
	ds_read2_b32 v[6:7], v103 offset0:66 offset1:99
	s_waitcnt lgkmcnt(0)
	v_cvt_pk_bf16_f32 v5, v6, v7
	ds_read2_b32 v[6:7], v103 offset0:132 offset1:165
	v_or_b32_e32 v2, s4, v97
	s_waitcnt lgkmcnt(0)
	v_cvt_pk_bf16_f32 v6, v6, v7
	ds_read2_b32 v[10:11], v103 offset0:198 offset1:231
	v_mul_u32_u24_e32 v2, 0x1600, v2
	s_waitcnt lgkmcnt(0)
	v_cvt_pk_bf16_f32 v7, v10, v11
	v_lshl_add_u64 v[10:11], v[8:9], 0, v[2:3]
	global_store_dwordx4 v[10:11], v[4:7], off sc1
	ds_read2_b32 v[4:5], v103 offset0:8 offset1:41
	v_or_b32_e32 v2, s4, v107
	s_waitcnt lgkmcnt(0)
	v_cvt_pk_bf16_f32 v4, v4, v5
	ds_read2_b32 v[6:7], v103 offset0:74 offset1:107
	s_waitcnt lgkmcnt(0)
	v_cvt_pk_bf16_f32 v5, v6, v7
	ds_read2_b32 v[6:7], v103 offset0:140 offset1:173
	s_waitcnt lgkmcnt(0)
	v_cvt_pk_bf16_f32 v6, v6, v7
	ds_read2_b32 v[10:11], v103 offset0:206 offset1:239
	v_mul_u32_u24_e32 v2, 0x1600, v2
	s_waitcnt lgkmcnt(0)
	v_cvt_pk_bf16_f32 v7, v10, v11
	v_lshl_add_u64 v[10:11], v[8:9], 0, v[2:3]
	global_store_dwordx4 v[10:11], v[4:7], off sc1
	ds_read2_b32 v[4:5], v103 offset0:16 offset1:49
	v_or_b32_e32 v2, s4, v109
	s_waitcnt lgkmcnt(0)
	v_cvt_pk_bf16_f32 v4, v4, v5
	ds_read2_b32 v[6:7], v103 offset0:82 offset1:115
	s_waitcnt lgkmcnt(0)
	v_cvt_pk_bf16_f32 v5, v6, v7
	ds_read2_b32 v[6:7], v103 offset0:148 offset1:181
	s_waitcnt lgkmcnt(0)
	v_cvt_pk_bf16_f32 v6, v6, v7
	ds_read2_b32 v[10:11], v103 offset0:214 offset1:247
	v_mul_u32_u24_e32 v2, 0x1600, v2
	s_waitcnt lgkmcnt(0)
	v_cvt_pk_bf16_f32 v7, v10, v11
	v_lshl_add_u64 v[10:11], v[8:9], 0, v[2:3]
	global_store_dwordx4 v[10:11], v[4:7], off sc1
	ds_read2_b32 v[4:5], v103 offset0:24 offset1:57
	v_or_b32_e32 v2, s4, v112
	s_waitcnt lgkmcnt(0)
	v_cvt_pk_bf16_f32 v4, v4, v5
	ds_read2_b32 v[6:7], v103 offset0:90 offset1:123
	v_mul_u32_u24_e32 v2, 0x1600, v2
	s_waitcnt lgkmcnt(0)
	v_cvt_pk_bf16_f32 v5, v6, v7
	ds_read2_b32 v[6:7], v103 offset0:156 offset1:189
	v_lshl_add_u64 v[8:9], v[8:9], 0, v[2:3]
	s_waitcnt lgkmcnt(0)
	v_cvt_pk_bf16_f32 v6, v6, v7
	ds_read2_b32 v[10:11], v103 offset0:222 offset1:255
	s_waitcnt lgkmcnt(0)
	v_cvt_pk_bf16_f32 v7, v10, v11
	global_store_dwordx4 v[8:9], v[4:7], off sc1
	s_waitcnt lgkmcnt(0)

; #define GAS __attribute__((address_space(1)))
; #define LAS __attribute__((address_space(3)))
; #define LDS_WAIT() asm volatile("s_waitcnt lgkmcnt(0)" ::: "memory")
; #define NTLOAD(p) __builtin_nontemporal_load(p)
; __device__ __forceinline__ void cv_item(const float* W, int N, const float* gk, bf16_t* WT, int ldt, int kofs, int drow, int kb, int nb, LAS float* scr, int lane) {
;     const int k0 = 64 * kb, n0 = 32 * nb, kq = lane >> 3, n4 = (lane & 7) * 4;
;     f32x4 v[8]; float sc[8];
; #pragma unroll
;     for (int i = 0; i < 8; ++i) { v[i] = NTLOAD((const GAS f32x4*)(W + (size_t)(k0 + 8 * i + kq) * N + n0 + n4)); sc[i] = gk ? gk[k0 + 8 * i + kq] : 1.0f; }
; #pragma unroll
;     for (int i = 0; i < 8; ++i) { LAS float* d = scr + (8 * i + kq) * 33 + n4; const f32x4 t = v[i] * sc[i]; d[0] = t[0]; d[1] = t[1]; d[2] = t[2]; d[3] = t[3]; }
;     LDS_WAIT(); asm volatile("" ::: "memory");
;     const int c = lane & 7;
; #pragma unroll
;     for (int j = 0; j < 4; ++j) { const int n = (lane >> 3) + 8 * j; const LAS float* s = scr + (8 * c) * 33 + n;
;         u32x4 o; o.x = pk2(s[0 * 33], s[1 * 33]); o.y = pk2(s[2 * 33], s[3 * 33]); o.z = pk2(s[4 * 33], s[5 * 33]); o.w = pk2(s[6 * 33], s[7 * 33]);
;         *(GAS u32x4*)(WT + (size_t)(drow + n) * ldt + kofs + k0 + 8 * c) = o; }
;     LDS_WAIT(); asm volatile("" ::: "memory");
; }
.LBB0_964:
	s_waitcnt vmcnt(7)
	v_pk_mul_f32 v[6:7], v[6:7], v[96:97] op_sel_hi:[1,0]
	v_pk_mul_f32 v[4:5], v[4:5], v[96:97] op_sel_hi:[1,0]
	v_add_u32_e32 v96, v99, v105
	ds_write2_b32 v96, v4, v5 offset1:1
	ds_write2_b32 v96, v6, v7 offset0:2 offset1:3
	s_waitcnt vmcnt(6)
	v_pk_mul_f32 v[4:5], v[10:11], v[2:3] op_sel_hi:[1,0]
	v_pk_mul_f32 v[6:7], v[8:9], v[2:3] op_sel_hi:[1,0]
	v_add_u32_e32 v2, 0x420, v96
	ds_write2_b32 v2, v6, v7 offset1:1
	v_add_u32_e32 v2, 0x428, v96
	ds_write2_b32 v2, v4, v5 offset1:1
	s_waitcnt vmcnt(5)
	v_pk_mul_f32 v[6:7], v[12:13], v[100:101] op_sel_hi:[1,0]
	v_add_u32_e32 v2, 0x840, v96
	v_pk_mul_f32 v[4:5], v[14:15], v[100:101] op_sel_hi:[1,0]
	ds_write2_b32 v2, v6, v7 offset1:1
	v_add_u32_e32 v2, 0x848, v96
	ds_write2_b32 v2, v4, v5 offset1:1
	s_waitcnt vmcnt(4)
	v_pk_mul_f32 v[6:7], v[16:17], v[98:99] op_sel_hi:[1,0]
	v_add_u32_e32 v2, 0xc60, v96
	v_pk_mul_f32 v[4:5], v[18:19], v[98:99] op_sel_hi:[1,0]
	ds_write2_b32 v2, v6, v7 offset1:1
	v_add_u32_e32 v2, 0xc68, v96
	ds_write2_b32 v2, v4, v5 offset1:1
	s_waitcnt vmcnt(3)
	v_pk_mul_f32 v[6:7], v[20:21], v[104:105] op_sel_hi:[1,0]
	v_add_u32_e32 v2, 0x1080, v96
	v_pk_mul_f32 v[4:5], v[22:23], v[104:105] op_sel_hi:[1,0]
	ds_write2_b32 v2, v6, v7 offset1:1
	v_add_u32_e32 v2, 0x1088, v96
	ds_write2_b32 v2, v4, v5 offset1:1
	s_waitcnt vmcnt(2)
	v_pk_mul_f32 v[6:7], v[24:25], v[102:103] op_sel_hi:[1,0]
	v_add_u32_e32 v2, 0x14a0, v96
	v_pk_mul_f32 v[4:5], v[26:27], v[102:103] op_sel_hi:[1,0]
	ds_write2_b32 v2, v6, v7 offset1:1
	v_add_u32_e32 v2, 0x14a8, v96
	ds_write2_b32 v2, v4, v5 offset1:1
	s_waitcnt vmcnt(1)
	v_pk_mul_f32 v[6:7], v[28:29], v[108:109] op_sel_hi:[1,0]
	v_add_u32_e32 v2, 0x18c0, v96
	v_pk_mul_f32 v[4:5], v[30:31], v[108:109] op_sel_hi:[1,0]
	ds_write2_b32 v2, v6, v7 offset1:1
	v_add_u32_e32 v2, 0x18c8, v96
	ds_write2_b32 v2, v4, v5 offset1:1
	s_waitcnt vmcnt(0)
	v_pk_mul_f32 v[6:7], v[32:33], v[106:107] op_sel_hi:[1,0]
	v_add_u32_e32 v2, 0x1ce0, v96
	v_pk_mul_f32 v[4:5], v[34:35], v[106:107] op_sel_hi:[1,0]
	ds_write2_b32 v2, v6, v7 offset1:1
	v_add_u32_e32 v2, 0x1ce8, v96
	ds_write2_b32 v2, v4, v5 offset1:1
	s_waitcnt lgkmcnt(0)
	ds_read2_b32 v[4:5], v103 offset1:33
	s_and_b32 s0, 0xffff, s8
	s_waitcnt lgkmcnt(0)
	v_cvt_pk_bf16_f32 v4, v4, v5
	ds_read2_b32 v[6:7], v103 offset0:66 offset1:99
	s_mov_b32 s9, s15
	s_lshl_b32 s8, s0, 1
	v_add_u32_e32 v2, s5, v97
	s_waitcnt lgkmcnt(0)
	v_cvt_pk_bf16_f32 v5, v6, v7
	ds_read2_b32 v[6:7], v103 offset0:132 offset1:165
	v_lshl_add_u64 v[10:11], v[82:83], 0, s[8:9]
	v_lshlrev_b64 v[12:13], 11, v[2:3]
	s_waitcnt lgkmcnt(0)
	v_cvt_pk_bf16_f32 v6, v6, v7
	ds_read2_b32 v[8:9], v103 offset0:198 offset1:231
	s_waitcnt lgkmcnt(0)
	v_cvt_pk_bf16_f32 v7, v8, v9
	v_lshl_add_u64 v[12:13], v[10:11], 0, v[12:13]
	ds_read2_b32 v[8:9], v103 offset0:8 offset1:41
	global_store_dwordx4 v[12:13], v[4:7], off sc1
	v_add_u32_e32 v2, s5, v107
	v_lshlrev_b64 v[12:13], 11, v[2:3]
	s_waitcnt lgkmcnt(0)
	v_cvt_pk_bf16_f32 v4, v8, v9
	ds_read2_b32 v[6:7], v103 offset0:74 offset1:107
	s_waitcnt lgkmcnt(0)
	v_cvt_pk_bf16_f32 v5, v6, v7
	ds_read2_b32 v[6:7], v103 offset0:140 offset1:173
	s_waitcnt lgkmcnt(0)
	v_cvt_pk_bf16_f32 v6, v6, v7
	ds_read2_b32 v[8:9], v103 offset0:206 offset1:239
	s_waitcnt lgkmcnt(0)
	v_cvt_pk_bf16_f32 v7, v8, v9
	v_lshl_add_u64 v[12:13], v[10:11], 0, v[12:13]
	ds_read2_b32 v[8:9], v103 offset0:16 offset1:49
	global_store_dwordx4 v[12:13], v[4:7], off sc1
	v_add_u32_e32 v2, s5, v109
	v_lshlrev_b64 v[12:13], 11, v[2:3]
	s_waitcnt lgkmcnt(0)
	v_cvt_pk_bf16_f32 v4, v8, v9
	ds_read2_b32 v[6:7], v103 offset0:82 offset1:115
	s_waitcnt lgkmcnt(0)
	v_cvt_pk_bf16_f32 v5, v6, v7
	ds_read2_b32 v[6:7], v103 offset0:148 offset1:181
	s_waitcnt lgkmcnt(0)
	v_cvt_pk_bf16_f32 v6, v6, v7
	ds_read2_b32 v[8:9], v103 offset0:214 offset1:247
	s_waitcnt lgkmcnt(0)
	v_cvt_pk_bf16_f32 v7, v8, v9
	v_lshl_add_u64 v[12:13], v[10:11], 0, v[12:13]
	ds_read2_b32 v[8:9], v103 offset0:24 offset1:57
	global_store_dwordx4 v[12:13], v[4:7], off sc1
	v_add_u32_e32 v2, s5, v112
	s_mov_b32 s1, s15
	s_waitcnt lgkmcnt(0)
	v_cvt_pk_bf16_f32 v4, v8, v9
	ds_read2_b32 v[6:7], v103 offset0:90 offset1:123
	s_waitcnt lgkmcnt(0)
	v_cvt_pk_bf16_f32 v5, v6, v7
	ds_read2_b32 v[6:7], v103 offset0:156 offset1:189
	s_waitcnt lgkmcnt(0)
	v_cvt_pk_bf16_f32 v6, v6, v7
	ds_read2_b32 v[8:9], v103 offset0:222 offset1:255
	s_waitcnt lgkmcnt(0)
	v_cvt_pk_bf16_f32 v7, v8, v9
	v_lshlrev_b64 v[8:9], 11, v[2:3]
	v_lshl_add_u64 v[8:9], v[10:11], 0, v[8:9]
	global_store_dwordx4 v[8:9], v[4:7], off sc1
	s_waitcnt lgkmcnt(0)
	v_writelane_b32 v254, s0, 4
	s_nop 1
	v_writelane_b32 v254, s1, 5
	s_mov_b64 s[0:1], 0
; #define GAS __attribute__((address_space(1)))
; #define LAS __attribute__((address_space(3)))
; #define LDS_WAIT() asm volatile("s_waitcnt lgkmcnt(0)" ::: "memory")
; #define NTLOAD(p) __builtin_nontemporal_load(p)
; __device__ __forceinline__ void cv_item(const float* W, int N, const float* gk, bf16_t* WT, int ldt, int kofs, int drow, int kb, int nb, LAS float* scr, int lane) {
;     const int k0 = 64 * kb, n0 = 32 * nb, kq = lane >> 3, n4 = (lane & 7) * 4;
;     f32x4 v[8]; float sc[8];
; #pragma unroll
;     for (int i = 0; i < 8; ++i) { v[i] = NTLOAD((const GAS f32x4*)(W + (size_t)(k0 + 8 * i + kq) * N + n0 + n4)); sc[i] = gk ? gk[k0 + 8 * i + kq] : 1.0f; }
; #pragma unroll
;     for (int i = 0; i < 8; ++i) { LAS float* d = scr + (8 * i + kq) * 33 + n4; const f32x4 t = v[i] * sc[i]; d[0] = t[0]; d[1] = t[1]; d[2] = t[2]; d[3] = t[3]; }
;     LDS_WAIT(); asm volatile("" ::: "memory");
;     const int c = lane & 7;
; #pragma unroll
;     for (int j = 0; j < 4; ++j) { const int n = (lane >> 3) + 8 * j; const LAS float* s = scr + (8 * c) * 33 + n;
;         u32x4 o; o.x = pk2(s[0 * 33], s[1 * 33]); o.y = pk2(s[2 * 33], s[3 * 33]); o.z = pk2(s[4 * 33], s[5 * 33]); o.w = pk2(s[6 * 33], s[7 * 33]);
;         *(GAS u32x4*)(WT + (size_t)(drow + n) * ldt + kofs + k0 + 8 * c) = o; }
;     LDS_WAIT(); asm volatile("" ::: "memory");
; }
; __device__ __forceinline__ void cv_dispatch(const CvPtrs& P, unsigned char* ws, float* out, int layer, int r, LAS float* scr, int lane) {
;     ...
;     if (r < CI_A)  { const int nblk = D / 32, kb = r / nblk, nb = r % nblk; cv_item(P.w_a + (size_t)layer * DC * D, D, nullptr, WB + WB_WAB, D, 0, 32 * nb, kb, nb, scr, lane); return; } r -= CI_A;
;     if (r < CI_A)  { const int nblk = D / 32, kb = r / nblk, nb = r % nblk; cv_item(P.w_b + (size_t)layer * DSC * D, D, nullptr, WB + WB_WAB, D, DC, 32 * nb, kb, nb, scr, lane); return; } r -= CI_A;
;     if (r < CI_O)  { const int nblk = D / 32, kb = r / nblk, nb = r % nblk; cv_item(P.w_o + (size_t)layer * D * D, D, nullptr, WB + WB_WO, D, 0, 32 * nb, kb, nb, scr, lane); return; } r -= CI_O;
.LBB0_965:
	s_and_b64 vcc, exec, s[0:1]
	s_cbranch_vccz .LBB0_967
	s_lshl_b32 s0, s4, 5
	s_and_b32 s5, s0, 0x3e0
	s_lshl_b32 s0, s4, 1
	s_and_b32 s0, s0, 0x1fc0
	s_addk_i32 s0, 0xea00
	v_or_b32_e32 v32, s0, v97
	v_readlane_b32 s8, v254, 4
	v_readlane_b32 s9, v254, 5
	s_lshl_b32 s8, s5, 2
	v_ashrrev_i32_e32 v33, 31, v32
	v_or_b32_e32 v8, 8, v32
	v_lshl_add_u64 v[34:35], v[44:45], 0, s[8:9]
	v_lshlrev_b64 v[4:5], 12, v[32:33]
	v_ashrrev_i32_e32 v9, 31, v8
	v_lshl_add_u64 v[4:5], v[34:35], 0, v[4:5]
	v_lshlrev_b64 v[8:9], 12, v[8:9]
	v_or_b32_e32 v12, 16, v32
	global_load_dwordx4 v[4:7], v[4:5], off nt
	v_lshl_add_u64 v[8:9], v[34:35], 0, v[8:9]
	v_ashrrev_i32_e32 v13, 31, v12
	global_load_dwordx4 v[8:11], v[8:9], off nt
	v_lshlrev_b64 v[12:13], 12, v[12:13]
	v_or_b32_e32 v16, 24, v32
	v_lshl_add_u64 v[12:13], v[34:35], 0, v[12:13]
	v_ashrrev_i32_e32 v17, 31, v16
	global_load_dwordx4 v[12:15], v[12:13], off nt
	v_lshlrev_b64 v[16:17], 12, v[16:17]
	v_or_b32_e32 v20, 32, v32
	v_lshl_add_u64 v[16:17], v[34:35], 0, v[16:17]
	v_ashrrev_i32_e32 v21, 31, v20
	global_load_dwordx4 v[16:19], v[16:17], off nt
	v_lshlrev_b64 v[20:21], 12, v[20:21]
	v_or_b32_e32 v24, 40, v32
	v_lshl_add_u64 v[20:21], v[34:35], 0, v[20:21]
	v_ashrrev_i32_e32 v25, 31, v24
	global_load_dwordx4 v[20:23], v[20:21], off nt
	v_lshlrev_b64 v[24:25], 12, v[24:25]
	v_or_b32_e32 v28, 48, v32
	v_lshl_add_u64 v[24:25], v[34:35], 0, v[24:25]
	v_ashrrev_i32_e32 v29, 31, v28
	global_load_dwordx4 v[24:27], v[24:25], off nt
	v_lshlrev_b64 v[28:29], 12, v[28:29]
	v_or_b32_e32 v32, 56, v32
	v_lshl_add_u64 v[28:29], v[34:35], 0, v[28:29]
	v_ashrrev_i32_e32 v33, 31, v32
	global_load_dwordx4 v[28:31], v[28:29], off nt
	v_lshlrev_b64 v[32:33], 12, v[32:33]
	v_lshl_add_u64 v[32:33], v[34:35], 0, v[32:33]
	global_load_dwordx4 v[32:35], v[32:33], off nt
	v_add_u32_e32 v2, v99, v105
	s_mov_b32 s1, s9
	v_writelane_b32 v254, s0, 4
	s_waitcnt vmcnt(7)
	ds_write2_b32 v2, v4, v5 offset1:1
	ds_write2_b32 v2, v6, v7 offset0:2 offset1:3
	v_add_u32_e32 v4, 0x420, v2
	v_writelane_b32 v254, s1, 5
	s_waitcnt vmcnt(6)
	ds_write2_b32 v4, v8, v9 offset1:1
	v_add_u32_e32 v4, 0x428, v2
	ds_write2_b32 v4, v10, v11 offset1:1
	v_add_u32_e32 v4, 0x840, v2
	s_mov_b32 s1, s9
	s_waitcnt vmcnt(5)
	ds_write2_b32 v4, v12, v13 offset1:1
	v_add_u32_e32 v4, 0x848, v2
	ds_write2_b32 v4, v14, v15 offset1:1
	v_add_u32_e32 v4, 0xc60, v2
	v_lshl_add_u64 v[8:9], s[0:1], 1, v[84:85]
	s_waitcnt vmcnt(4)
	ds_write2_b32 v4, v16, v17 offset1:1
	v_add_u32_e32 v4, 0xc68, v2
	ds_write2_b32 v4, v18, v19 offset1:1
	v_add_u32_e32 v4, 0x1080, v2
	s_waitcnt vmcnt(3)
	ds_write2_b32 v4, v20, v21 offset1:1
	v_add_u32_e32 v4, 0x1088, v2
	ds_write2_b32 v4, v22, v23 offset1:1
	v_add_u32_e32 v4, 0x14a0, v2
	s_waitcnt vmcnt(2)
	ds_write2_b32 v4, v24, v25 offset1:1
	v_add_u32_e32 v4, 0x14a8, v2
	ds_write2_b32 v4, v26, v27 offset1:1
	v_add_u32_e32 v4, 0x18c0, v2
	s_waitcnt vmcnt(1)
	ds_write2_b32 v4, v28, v29 offset1:1
	v_add_u32_e32 v4, 0x18c8, v2
	ds_write2_b32 v4, v30, v31 offset1:1
	v_add_u32_e32 v4, 0x1ce0, v2
	v_add_u32_e32 v2, 0x1ce8, v2
	s_waitcnt vmcnt(0)
	ds_write2_b32 v4, v32, v33 offset1:1
	ds_write2_b32 v2, v34, v35 offset1:1
	s_waitcnt lgkmcnt(0)
	ds_read2_b32 v[4:5], v103 offset1:33
	s_waitcnt lgkmcnt(0)
	v_cvt_pk_bf16_f32 v4, v4, v5
	ds_read2_b32 v[6:7], v103 offset0:66 offset1:99
	s_waitcnt lgkmcnt(0)
	v_cvt_pk_bf16_f32 v5, v6, v7
	ds_read2_b32 v[6:7], v103 offset0:132 offset1:165
	v_or_b32_e32 v2, s5, v97
	s_waitcnt lgkmcnt(0)
	v_cvt_pk_bf16_f32 v6, v6, v7
	ds_read2_b32 v[10:11], v103 offset0:198 offset1:231
	v_lshlrev_b32_e32 v2, 11, v2
	s_waitcnt lgkmcnt(0)
	v_cvt_pk_bf16_f32 v7, v10, v11
	v_lshl_add_u64 v[10:11], v[8:9], 0, v[2:3]
	global_store_dwordx4 v[10:11], v[4:7], off sc1
	ds_read2_b32 v[4:5], v103 offset0:8 offset1:41
	v_or_b32_e32 v2, s5, v107
	s_waitcnt lgkmcnt(0)
	v_cvt_pk_bf16_f32 v4, v4, v5
	ds_read2_b32 v[6:7], v103 offset0:74 offset1:107
	s_waitcnt lgkmcnt(0)
	v_cvt_pk_bf16_f32 v5, v6, v7
	ds_read2_b32 v[6:7], v103 offset0:140 offset1:173
	s_waitcnt lgkmcnt(0)
	v_cvt_pk_bf16_f32 v6, v6, v7
	ds_read2_b32 v[10:11], v103 offset0:206 offset1:239
	v_lshlrev_b32_e32 v2, 11, v2
	s_waitcnt lgkmcnt(0)
	v_cvt_pk_bf16_f32 v7, v10, v11
	v_lshl_add_u64 v[10:11], v[8:9], 0, v[2:3]
	global_store_dwordx4 v[10:11], v[4:7], off sc1
	ds_read2_b32 v[4:5], v103 offset0:16 offset1:49
	v_or_b32_e32 v2, s5, v109
	s_waitcnt lgkmcnt(0)
	v_cvt_pk_bf16_f32 v4, v4, v5
	ds_read2_b32 v[6:7], v103 offset0:82 offset1:115
	s_waitcnt lgkmcnt(0)
	v_cvt_pk_bf16_f32 v5, v6, v7
	ds_read2_b32 v[6:7], v103 offset0:148 offset1:181
	s_waitcnt lgkmcnt(0)
	v_cvt_pk_bf16_f32 v6, v6, v7
	ds_read2_b32 v[10:11], v103 offset0:214 offset1:247
	v_lshlrev_b32_e32 v2, 11, v2
	s_waitcnt lgkmcnt(0)
	v_cvt_pk_bf16_f32 v7, v10, v11
	v_lshl_add_u64 v[10:11], v[8:9], 0, v[2:3]
	global_store_dwordx4 v[10:11], v[4:7], off sc1
	ds_read2_b32 v[4:5], v103 offset0:24 offset1:57
	v_or_b32_e32 v2, s5, v112
	s_waitcnt lgkmcnt(0)
	v_cvt_pk_bf16_f32 v4, v4, v5
	ds_read2_b32 v[6:7], v103 offset0:90 offset1:123
	v_lshlrev_b32_e32 v2, 11, v2
	s_waitcnt lgkmcnt(0)
	v_cvt_pk_bf16_f32 v5, v6, v7
	ds_read2_b32 v[6:7], v103 offset0:156 offset1:189
	v_lshl_add_u64 v[8:9], v[8:9], 0, v[2:3]
	s_waitcnt lgkmcnt(0)
	v_cvt_pk_bf16_f32 v6, v6, v7
	ds_read2_b32 v[10:11], v103 offset0:222 offset1:255
	s_waitcnt lgkmcnt(0)
	v_cvt_pk_bf16_f32 v7, v10, v11
	global_store_dwordx4 v[8:9], v[4:7], off sc1
	s_waitcnt lgkmcnt(0)

; #define GAS __attribute__((address_space(1)))
; #define LAS __attribute__((address_space(3)))
; #define LDS_WAIT() asm volatile("s_waitcnt lgkmcnt(0)" ::: "memory")
; #define NTLOAD(p) __builtin_nontemporal_load(p)
; __device__ __forceinline__ void cv_item(const float* W, int N, const float* gk, bf16_t* WT, int ldt, int kofs, int drow, int kb, int nb, LAS float* scr, int lane) {
;     const int k0 = 64 * kb, n0 = 32 * nb, kq = lane >> 3, n4 = (lane & 7) * 4;
;     f32x4 v[8]; float sc[8];
; #pragma unroll
;     for (int i = 0; i < 8; ++i) { v[i] = NTLOAD((const GAS f32x4*)(W + (size_t)(k0 + 8 * i + kq) * N + n0 + n4)); sc[i] = gk ? gk[k0 + 8 * i + kq] : 1.0f; }
; #pragma unroll
;     for (int i = 0; i < 8; ++i) { LAS float* d = scr + (8 * i + kq) * 33 + n4; const f32x4 t = v[i] * sc[i]; d[0] = t[0]; d[1] = t[1]; d[2] = t[2]; d[3] = t[3]; }
;     LDS_WAIT(); asm volatile("" ::: "memory");
;     const int c = lane & 7;
; #pragma unroll
;     for (int j = 0; j < 4; ++j) { const int n = (lane >> 3) + 8 * j; const LAS float* s = scr + (8 * c) * 33 + n;
;         u32x4 o; o.x = pk2(s[0 * 33], s[1 * 33]); o.y = pk2(s[2 * 33], s[3 * 33]); o.z = pk2(s[4 * 33], s[5 * 33]); o.w = pk2(s[6 * 33], s[7 * 33]);
;         *(GAS u32x4*)(WT + (size_t)(drow + n) * ldt + kofs + k0 + 8 * c) = o; }
;     LDS_WAIT(); asm volatile("" ::: "memory");
; }
; __device__ __forceinline__ void cv_dispatch(const CvPtrs& P, unsigned char* ws, float* out, int layer, int r, LAS float* scr, int lane) {
;     ...
;     if (r < CI_A)  { const int nblk = D / 32, kb = r / nblk, nb = r % nblk; cv_item(P.w_a + (size_t)layer * DC * D, D, nullptr, WB + WB_WAB, D, 0, 32 * nb, kb, nb, scr, lane); return; } r -= CI_A;
;     if (r < CI_A)  { const int nblk = D / 32, kb = r / nblk, nb = r % nblk; cv_item(P.w_b + (size_t)layer * DSC * D, D, nullptr, WB + WB_WAB, D, DC, 32 * nb, kb, nb, scr, lane); return; } r -= CI_A;
;     if (r < CI_O)  { const int nblk = D / 32, kb = r / nblk, nb = r % nblk; cv_item(P.w_o + (size_t)layer * D * D, D, nullptr, WB + WB_WO, D, 0, 32 * nb, kb, nb, scr, lane); return; } r -= CI_O;
.LBB0_968:
	s_andn2_b64 vcc, exec, s[0:1]
	s_cbranch_vccnz .LBB0_970
	s_lshl_b32 s0, s4, 5
	s_and_b32 s5, s0, 0x3e0
	s_lshl_b32 s0, s4, 1
	s_and_b32 s0, s0, 0x1fc0
	s_addk_i32 s0, 0xec00
	v_or_b32_e32 v32, s0, v97
	v_readlane_b32 s8, v254, 4
	v_readlane_b32 s9, v254, 5
	s_lshl_b32 s8, s5, 2
	v_ashrrev_i32_e32 v33, 31, v32
	v_or_b32_e32 v8, 8, v32
	v_lshl_add_u64 v[34:35], v[46:47], 0, s[8:9]
	v_lshlrev_b64 v[4:5], 12, v[32:33]
	v_ashrrev_i32_e32 v9, 31, v8
	v_lshl_add_u64 v[4:5], v[34:35], 0, v[4:5]
	v_lshlrev_b64 v[8:9], 12, v[8:9]
	v_or_b32_e32 v12, 16, v32
	global_load_dwordx4 v[4:7], v[4:5], off nt
	v_lshl_add_u64 v[8:9], v[34:35], 0, v[8:9]
	v_ashrrev_i32_e32 v13, 31, v12
	global_load_dwordx4 v[8:11], v[8:9], off nt
	v_lshlrev_b64 v[12:13], 12, v[12:13]
	v_or_b32_e32 v16, 24, v32
	v_lshl_add_u64 v[12:13], v[34:35], 0, v[12:13]
	v_ashrrev_i32_e32 v17, 31, v16
	global_load_dwordx4 v[12:15], v[12:13], off nt
	v_lshlrev_b64 v[16:17], 12, v[16:17]
	v_or_b32_e32 v20, 32, v32
	v_lshl_add_u64 v[16:17], v[34:35], 0, v[16:17]
	v_ashrrev_i32_e32 v21, 31, v20
	global_load_dwordx4 v[16:19], v[16:17], off nt
	v_lshlrev_b64 v[20:21], 12, v[20:21]
	v_or_b32_e32 v24, 40, v32
	v_lshl_add_u64 v[20:21], v[34:35], 0, v[20:21]
	v_ashrrev_i32_e32 v25, 31, v24
	global_load_dwordx4 v[20:23], v[20:21], off nt
	v_lshlrev_b64 v[24:25], 12, v[24:25]
	v_or_b32_e32 v28, 48, v32
	v_lshl_add_u64 v[24:25], v[34:35], 0, v[24:25]
	v_ashrrev_i32_e32 v29, 31, v28
	global_load_dwordx4 v[24:27], v[24:25], off nt
	v_lshlrev_b64 v[28:29], 12, v[28:29]
	v_or_b32_e32 v32, 56, v32
	v_lshl_add_u64 v[28:29], v[34:35], 0, v[28:29]
	v_ashrrev_i32_e32 v33, 31, v32
	global_load_dwordx4 v[28:31], v[28:29], off nt
	v_lshlrev_b64 v[32:33], 12, v[32:33]
	v_lshl_add_u64 v[32:33], v[34:35], 0, v[32:33]
	global_load_dwordx4 v[32:35], v[32:33], off nt
	v_add_u32_e32 v2, v99, v105
	s_mov_b32 s1, s9
	v_writelane_b32 v254, s0, 4
	s_waitcnt vmcnt(7)
	ds_write2_b32 v2, v4, v5 offset1:1
	ds_write2_b32 v2, v6, v7 offset0:2 offset1:3
	v_add_u32_e32 v4, 0x420, v2
	v_writelane_b32 v254, s1, 5
	s_waitcnt vmcnt(6)
	ds_write2_b32 v4, v8, v9 offset1:1
	v_add_u32_e32 v4, 0x428, v2
	ds_write2_b32 v4, v10, v11 offset1:1
	v_add_u32_e32 v4, 0x840, v2
	s_mov_b32 s1, s9
	s_waitcnt vmcnt(5)
	ds_write2_b32 v4, v12, v13 offset1:1
	v_add_u32_e32 v4, 0x848, v2
	ds_write2_b32 v4, v14, v15 offset1:1
	v_add_u32_e32 v4, 0xc60, v2
	v_lshl_add_u64 v[8:9], s[0:1], 1, v[86:87]
	s_waitcnt vmcnt(4)
	ds_write2_b32 v4, v16, v17 offset1:1
	v_add_u32_e32 v4, 0xc68, v2
	ds_write2_b32 v4, v18, v19 offset1:1
	v_add_u32_e32 v4, 0x1080, v2
	s_waitcnt vmcnt(3)
	ds_write2_b32 v4, v20, v21 offset1:1
	v_add_u32_e32 v4, 0x1088, v2
	ds_write2_b32 v4, v22, v23 offset1:1
	v_add_u32_e32 v4, 0x14a0, v2
	s_waitcnt vmcnt(2)
	ds_write2_b32 v4, v24, v25 offset1:1
	v_add_u32_e32 v4, 0x14a8, v2
	ds_write2_b32 v4, v26, v27 offset1:1
	v_add_u32_e32 v4, 0x18c0, v2
	s_waitcnt vmcnt(1)
	ds_write2_b32 v4, v28, v29 offset1:1
	v_add_u32_e32 v4, 0x18c8, v2
	ds_write2_b32 v4, v30, v31 offset1:1
	v_add_u32_e32 v4, 0x1ce0, v2
	v_add_u32_e32 v2, 0x1ce8, v2
	s_waitcnt vmcnt(0)
	ds_write2_b32 v4, v32, v33 offset1:1
	ds_write2_b32 v2, v34, v35 offset1:1
	s_waitcnt lgkmcnt(0)
	ds_read2_b32 v[4:5], v103 offset1:33
	s_waitcnt lgkmcnt(0)
	v_cvt_pk_bf16_f32 v4, v4, v5
	ds_read2_b32 v[6:7], v103 offset0:66 offset1:99
	s_waitcnt lgkmcnt(0)
	v_cvt_pk_bf16_f32 v5, v6, v7
	ds_read2_b32 v[6:7], v103 offset0:132 offset1:165
	v_or_b32_e32 v2, s5, v97
	s_waitcnt lgkmcnt(0)
	v_cvt_pk_bf16_f32 v6, v6, v7
	ds_read2_b32 v[10:11], v103 offset0:198 offset1:231
	v_lshlrev_b32_e32 v2, 11, v2
	s_waitcnt lgkmcnt(0)
	v_cvt_pk_bf16_f32 v7, v10, v11
	v_lshl_add_u64 v[10:11], v[8:9], 0, v[2:3]
	global_store_dwordx4 v[10:11], v[4:7], off sc1
	ds_read2_b32 v[4:5], v103 offset0:8 offset1:41
	v_or_b32_e32 v2, s5, v107
	s_waitcnt lgkmcnt(0)
	v_cvt_pk_bf16_f32 v4, v4, v5
	ds_read2_b32 v[6:7], v103 offset0:74 offset1:107
	s_waitcnt lgkmcnt(0)
	v_cvt_pk_bf16_f32 v5, v6, v7
	ds_read2_b32 v[6:7], v103 offset0:140 offset1:173
	s_waitcnt lgkmcnt(0)
	v_cvt_pk_bf16_f32 v6, v6, v7
	ds_read2_b32 v[10:11], v103 offset0:206 offset1:239
	v_lshlrev_b32_e32 v2, 11, v2
	s_waitcnt lgkmcnt(0)
	v_cvt_pk_bf16_f32 v7, v10, v11
	v_lshl_add_u64 v[10:11], v[8:9], 0, v[2:3]
	global_store_dwordx4 v[10:11], v[4:7], off sc1
	ds_read2_b32 v[4:5], v103 offset0:16 offset1:49
	v_or_b32_e32 v2, s5, v109
	s_waitcnt lgkmcnt(0)
	v_cvt_pk_bf16_f32 v4, v4, v5
	ds_read2_b32 v[6:7], v103 offset0:82 offset1:115
	s_waitcnt lgkmcnt(0)
	v_cvt_pk_bf16_f32 v5, v6, v7
	ds_read2_b32 v[6:7], v103 offset0:148 offset1:181
	s_waitcnt lgkmcnt(0)
	v_cvt_pk_bf16_f32 v6, v6, v7
	ds_read2_b32 v[10:11], v103 offset0:214 offset1:247
	v_lshlrev_b32_e32 v2, 11, v2
	s_waitcnt lgkmcnt(0)
	v_cvt_pk_bf16_f32 v7, v10, v11
	v_lshl_add_u64 v[10:11], v[8:9], 0, v[2:3]
	global_store_dwordx4 v[10:11], v[4:7], off sc1
	ds_read2_b32 v[4:5], v103 offset0:24 offset1:57
	v_or_b32_e32 v2, s5, v112
	s_waitcnt lgkmcnt(0)
	v_cvt_pk_bf16_f32 v4, v4, v5
	ds_read2_b32 v[6:7], v103 offset0:90 offset1:123
	v_lshlrev_b32_e32 v2, 11, v2
	s_waitcnt lgkmcnt(0)
	v_cvt_pk_bf16_f32 v5, v6, v7
	ds_read2_b32 v[6:7], v103 offset0:156 offset1:189
	v_lshl_add_u64 v[8:9], v[8:9], 0, v[2:3]
	s_waitcnt lgkmcnt(0)
	v_cvt_pk_bf16_f32 v6, v6, v7
	ds_read2_b32 v[10:11], v103 offset0:222 offset1:255
	s_waitcnt lgkmcnt(0)
	v_cvt_pk_bf16_f32 v7, v10, v11
	global_store_dwordx4 v[8:9], v[4:7], off sc1
	s_waitcnt lgkmcnt(0)

; #define GAS __attribute__((address_space(1)))
; #define LAS __attribute__((address_space(3)))
; #define LDS_WAIT() asm volatile("s_waitcnt lgkmcnt(0)" ::: "memory")
; #define NTLOAD(p) __builtin_nontemporal_load(p)
; __device__ __forceinline__ void cv_item(const float* W, int N, const float* gk, bf16_t* WT, int ldt, int kofs, int drow, int kb, int nb, LAS float* scr, int lane) {
;     const int k0 = 64 * kb, n0 = 32 * nb, kq = lane >> 3, n4 = (lane & 7) * 4;
;     f32x4 v[8]; float sc[8];
; #pragma unroll
;     for (int i = 0; i < 8; ++i) { v[i] = NTLOAD((const GAS f32x4*)(W + (size_t)(k0 + 8 * i + kq) * N + n0 + n4)); sc[i] = gk ? gk[k0 + 8 * i + kq] : 1.0f; }
; #pragma unroll
;     for (int i = 0; i < 8; ++i) { LAS float* d = scr + (8 * i + kq) * 33 + n4; const f32x4 t = v[i] * sc[i]; d[0] = t[0]; d[1] = t[1]; d[2] = t[2]; d[3] = t[3]; }
;     LDS_WAIT(); asm volatile("" ::: "memory");
;     const int c = lane & 7;
; #pragma unroll
;     for (int j = 0; j < 4; ++j) { const int n = (lane >> 3) + 8 * j; const LAS float* s = scr + (8 * c) * 33 + n;
;         u32x4 o; o.x = pk2(s[0 * 33], s[1 * 33]); o.y = pk2(s[2 * 33], s[3 * 33]); o.z = pk2(s[4 * 33], s[5 * 33]); o.w = pk2(s[6 * 33], s[7 * 33]);
;         *(GAS u32x4*)(WT + (size_t)(drow + n) * ldt + kofs + k0 + 8 * c) = o; }
;     LDS_WAIT(); asm volatile("" ::: "memory");
; }
; __device__ __forceinline__ void cv_dispatch(const CvPtrs& P, unsigned char* ws, float* out, int layer, int r, LAS float* scr, int lane) {
;     ...
;     if (r < CI_A)  { const int nblk = D / 32, kb = r / nblk, nb = r % nblk; cv_item(P.w_a + (size_t)layer * DC * D, D, nullptr, WB + WB_WAB, D, 0, 32 * nb, kb, nb, scr, lane); return; } r -= CI_A;
;     if (r < CI_A)  { const int nblk = D / 32, kb = r / nblk, nb = r % nblk; cv_item(P.w_b + (size_t)layer * DSC * D, D, nullptr, WB + WB_WAB, D, DC, 32 * nb, kb, nb, scr, lane); return; } r -= CI_A;
;     if (r < CI_O)  { const int nblk = D / 32, kb = r / nblk, nb = r % nblk; cv_item(P.w_o + (size_t)layer * D * D, D, nullptr, WB + WB_WO, D, 0, 32 * nb, kb, nb, scr, lane); return; } r -= CI_O;
.LBB0_971:
	s_andn2_b64 vcc, exec, s[0:1]
	s_cbranch_vccnz .LBB0_973
	s_lshl_b32 s0, s4, 5
	s_and_b32 s5, s0, 0x3e0
	s_lshl_b32 s0, s4, 1
	s_and_b32 s0, s0, 0x1fc0
	s_addk_i32 s0, 0xee00
	v_or_b32_e32 v32, s0, v97
	v_readlane_b32 s8, v254, 4
	v_readlane_b32 s9, v254, 5
	s_lshl_b32 s8, s5, 2
	v_ashrrev_i32_e32 v33, 31, v32
	v_or_b32_e32 v8, 8, v32
	v_lshl_add_u64 v[34:35], v[48:49], 0, s[8:9]
	v_lshlrev_b64 v[4:5], 12, v[32:33]
	v_ashrrev_i32_e32 v9, 31, v8
	v_lshl_add_u64 v[4:5], v[34:35], 0, v[4:5]
	v_lshlrev_b64 v[8:9], 12, v[8:9]
	v_or_b32_e32 v12, 16, v32
	global_load_dwordx4 v[4:7], v[4:5], off nt
	v_lshl_add_u64 v[8:9], v[34:35], 0, v[8:9]
	v_ashrrev_i32_e32 v13, 31, v12
	global_load_dwordx4 v[8:11], v[8:9], off nt
	v_lshlrev_b64 v[12:13], 12, v[12:13]
	v_or_b32_e32 v16, 24, v32
	v_lshl_add_u64 v[12:13], v[34:35], 0, v[12:13]
	v_ashrrev_i32_e32 v17, 31, v16
	global_load_dwordx4 v[12:15], v[12:13], off nt
	v_lshlrev_b64 v[16:17], 12, v[16:17]
	v_or_b32_e32 v20, 32, v32
	v_lshl_add_u64 v[16:17], v[34:35], 0, v[16:17]
	v_ashrrev_i32_e32 v21, 31, v20
	global_load_dwordx4 v[16:19], v[16:17], off nt
	v_lshlrev_b64 v[20:21], 12, v[20:21]
	v_or_b32_e32 v24, 40, v32
	v_lshl_add_u64 v[20:21], v[34:35], 0, v[20:21]
	v_ashrrev_i32_e32 v25, 31, v24
	global_load_dwordx4 v[20:23], v[20:21], off nt
	v_lshlrev_b64 v[24:25], 12, v[24:25]
	v_or_b32_e32 v28, 48, v32
	v_lshl_add_u64 v[24:25], v[34:35], 0, v[24:25]
	v_ashrrev_i32_e32 v29, 31, v28
	global_load_dwordx4 v[24:27], v[24:25], off nt
	v_lshlrev_b64 v[28:29], 12, v[28:29]
	v_or_b32_e32 v32, 56, v32
	v_lshl_add_u64 v[28:29], v[34:35], 0, v[28:29]
	v_ashrrev_i32_e32 v33, 31, v32
	global_load_dwordx4 v[28:31], v[28:29], off nt
	v_lshlrev_b64 v[32:33], 12, v[32:33]
	v_lshl_add_u64 v[32:33], v[34:35], 0, v[32:33]
	global_load_dwordx4 v[32:35], v[32:33], off nt
	v_add_u32_e32 v2, v99, v105
	s_mov_b32 s1, s9
	v_writelane_b32 v254, s0, 4
	s_waitcnt vmcnt(7)
	ds_write2_b32 v2, v4, v5 offset1:1
	ds_write2_b32 v2, v6, v7 offset0:2 offset1:3
	v_add_u32_e32 v4, 0x420, v2
	v_writelane_b32 v254, s1, 5
	s_waitcnt vmcnt(6)
	ds_write2_b32 v4, v8, v9 offset1:1
	v_add_u32_e32 v4, 0x428, v2
	ds_write2_b32 v4, v10, v11 offset1:1
	v_add_u32_e32 v4, 0x840, v2
	s_mov_b32 s1, s9
	s_waitcnt vmcnt(5)
	ds_write2_b32 v4, v12, v13 offset1:1
	v_add_u32_e32 v4, 0x848, v2
	ds_write2_b32 v4, v14, v15 offset1:1
	v_add_u32_e32 v4, 0xc60, v2
	v_lshl_add_u64 v[8:9], s[0:1], 1, v[88:89]
	s_waitcnt vmcnt(4)
	ds_write2_b32 v4, v16, v17 offset1:1
	v_add_u32_e32 v4, 0xc68, v2
	ds_write2_b32 v4, v18, v19 offset1:1
	v_add_u32_e32 v4, 0x1080, v2
	s_waitcnt vmcnt(3)
	ds_write2_b32 v4, v20, v21 offset1:1
	v_add_u32_e32 v4, 0x1088, v2
	ds_write2_b32 v4, v22, v23 offset1:1
	v_add_u32_e32 v4, 0x14a0, v2
	s_waitcnt vmcnt(2)
	ds_write2_b32 v4, v24, v25 offset1:1
	v_add_u32_e32 v4, 0x14a8, v2
	ds_write2_b32 v4, v26, v27 offset1:1
	v_add_u32_e32 v4, 0x18c0, v2
	s_waitcnt vmcnt(1)
	ds_write2_b32 v4, v28, v29 offset1:1
	v_add_u32_e32 v4, 0x18c8, v2
	ds_write2_b32 v4, v30, v31 offset1:1
	v_add_u32_e32 v4, 0x1ce0, v2
	v_add_u32_e32 v2, 0x1ce8, v2
	s_waitcnt vmcnt(0)
	ds_write2_b32 v4, v32, v33 offset1:1
	ds_write2_b32 v2, v34, v35 offset1:1
	s_waitcnt lgkmcnt(0)
	ds_read2_b32 v[4:5], v103 offset1:33
	s_waitcnt lgkmcnt(0)
	v_cvt_pk_bf16_f32 v4, v4, v5
	ds_read2_b32 v[6:7], v103 offset0:66 offset1:99
	s_waitcnt lgkmcnt(0)
	v_cvt_pk_bf16_f32 v5, v6, v7
	ds_read2_b32 v[6:7], v103 offset0:132 offset1:165
	v_or_b32_e32 v2, s5, v97
	s_waitcnt lgkmcnt(0)
	v_cvt_pk_bf16_f32 v6, v6, v7
	ds_read2_b32 v[10:11], v103 offset0:198 offset1:231
	v_lshlrev_b32_e32 v2, 11, v2
	s_waitcnt lgkmcnt(0)
	v_cvt_pk_bf16_f32 v7, v10, v11
	v_lshl_add_u64 v[10:11], v[8:9], 0, v[2:3]
	global_store_dwordx4 v[10:11], v[4:7], off sc1
	ds_read2_b32 v[4:5], v103 offset0:8 offset1:41
	v_or_b32_e32 v2, s5, v107
	s_waitcnt lgkmcnt(0)
	v_cvt_pk_bf16_f32 v4, v4, v5
	ds_read2_b32 v[6:7], v103 offset0:74 offset1:107
	s_waitcnt lgkmcnt(0)
	v_cvt_pk_bf16_f32 v5, v6, v7
	ds_read2_b32 v[6:7], v103 offset0:140 offset1:173
	s_waitcnt lgkmcnt(0)
	v_cvt_pk_bf16_f32 v6, v6, v7
	ds_read2_b32 v[10:11], v103 offset0:206 offset1:239
	v_lshlrev_b32_e32 v2, 11, v2
	s_waitcnt lgkmcnt(0)
	v_cvt_pk_bf16_f32 v7, v10, v11
	v_lshl_add_u64 v[10:11], v[8:9], 0, v[2:3]
	global_store_dwordx4 v[10:11], v[4:7], off sc1
	ds_read2_b32 v[4:5], v103 offset0:16 offset1:49
	v_or_b32_e32 v2, s5, v109
	s_waitcnt lgkmcnt(0)
	v_cvt_pk_bf16_f32 v4, v4, v5
	ds_read2_b32 v[6:7], v103 offset0:82 offset1:115
	s_waitcnt lgkmcnt(0)
	v_cvt_pk_bf16_f32 v5, v6, v7
	ds_read2_b32 v[6:7], v103 offset0:148 offset1:181
	s_waitcnt lgkmcnt(0)
	v_cvt_pk_bf16_f32 v6, v6, v7
	ds_read2_b32 v[10:11], v103 offset0:214 offset1:247
	v_lshlrev_b32_e32 v2, 11, v2
	s_waitcnt lgkmcnt(0)
	v_cvt_pk_bf16_f32 v7, v10, v11
	v_lshl_add_u64 v[10:11], v[8:9], 0, v[2:3]
	global_store_dwordx4 v[10:11], v[4:7], off sc1
	ds_read2_b32 v[4:5], v103 offset0:24 offset1:57
	v_or_b32_e32 v2, s5, v112
	s_waitcnt lgkmcnt(0)
	v_cvt_pk_bf16_f32 v4, v4, v5
	ds_read2_b32 v[6:7], v103 offset0:90 offset1:123
	v_lshlrev_b32_e32 v2, 11, v2
	s_waitcnt lgkmcnt(0)
	v_cvt_pk_bf16_f32 v5, v6, v7
	ds_read2_b32 v[6:7], v103 offset0:156 offset1:189
	v_lshl_add_u64 v[8:9], v[8:9], 0, v[2:3]
	s_waitcnt lgkmcnt(0)
	v_cvt_pk_bf16_f32 v6, v6, v7
	ds_read2_b32 v[10:11], v103 offset0:222 offset1:255
	s_waitcnt lgkmcnt(0)
	v_cvt_pk_bf16_f32 v7, v10, v11
	global_store_dwordx4 v[8:9], v[4:7], off sc1
	s_waitcnt lgkmcnt(0)
